# hand-written pooling (register-resident window, 1 load round trip per 8 rows) in P2 slack replaces compiler pooling loop; + bias hoist + adaLN deferral
# baseline (speedup 1.0000x reference)
; #define GAS __attribute__((address_space(1)))
; __device__ __forceinline__ void prep_phase(Frame& F, CArgs a, int l, unsigned long long& tm_acc) {
;     ...
;         GAS bf16_t* P = (GAS bf16_t*)(ws + WS_POOL);
;         const int gw = F.blk * 8 + F.wave, NGW = F.G * 8;
;         for (int wi = gw; wi < M; wi += NGW) {
;             const int g = wi & 3, row = (wi >> 2) * 4 + (F.lane >> 4), cg = g * 16 + (F.lane & 15);
;             int t, L; if (row < MC) { t = row & 255; L = CTXL; } else { t = (row - MC) & 2047; L = SEQ; }
;             const GAS bf16_t* zc = Z + (size_t)(row - t) * DIN + cg * 8;
;             float s[8] = {0.f, 0.f, 0.f, 0.f, 0.f, 0.f, 0.f, 0.f}; int cnt = 0;
;             auto body = [&](auto WC) { constexpr int W = decltype(WC)::value;
;                 u32x4 v[W]; float mk[W];
; #pragma unroll
;                 for (int j = 0; j < W; ++j) { const int tt = t - W / 2 + j; const bool ok = tt >= 0 && tt < L; mk[j] = ok ? 1.f : 0.f; cnt += ok ? 1 : 0; v[j] = *(const GAS u32x4*)(zc + (size_t)(ok ? tt : t) * DIN); }
; #pragma unroll
;                 for (int j = 0; j < W; ++j) { s[0] += mk[j] * bflo(v[j].x); s[1] += mk[j] * bfhi(v[j].x); s[2] += mk[j] * bflo(v[j].y); s[3] += mk[j] * bfhi(v[j].y);
;                     s[4] += mk[j] * bflo(v[j].z); s[5] += mk[j] * bfhi(v[j].z); s[6] += mk[j] * bflo(v[j].w); s[7] += mk[j] * bfhi(v[j].w); } };
;             if (g == 0) body(std::integral_constant<int, 2>{}); else if (g == 1) body(std::integral_constant<int, 4>{}); else if (g == 2) body(std::integral_constant<int, 8>{}); else body(std::integral_constant<int, 16>{});
.LBB0_920:
	s_cmpk_lt_i32 s2, 32
	s_cbranch_scc1 .Lhp_skip
	v_writelane_b32 v201, s4, 0
	v_writelane_b32 v201, s5, 1
	v_writelane_b32 v201, s6, 2
	v_writelane_b32 v201, s7, 3
	v_writelane_b32 v201, s8, 4
	v_writelane_b32 v201, s9, 5
	v_writelane_b32 v201, s10, 6
	v_writelane_b32 v201, s11, 7
	v_writelane_b32 v201, s12, 8
	v_writelane_b32 v201, s13, 9
	v_writelane_b32 v201, s14, 10
	v_writelane_b32 v201, s15, 11
	v_writelane_b32 v201, s16, 12
	v_writelane_b32 v201, s17, 13
	v_writelane_b32 v201, s18, 14
	v_writelane_b32 v201, s19, 15
	v_writelane_b32 v201, s20, 16
	v_writelane_b32 v201, s21, 17
	v_writelane_b32 v201, s22, 18
	v_writelane_b32 v201, s23, 19
	v_writelane_b32 v201, s24, 20
	v_writelane_b32 v201, s25, 21
	v_writelane_b32 v201, s26, 22
	v_writelane_b32 v201, s27, 23
	v_writelane_b32 v201, s28, 24
	v_writelane_b32 v201, s29, 25
	v_writelane_b32 v201, s30, 26
	v_writelane_b32 v201, s31, 27
	v_readfirstlane_b32 s4, v0
	s_lshr_b32 s4, s4, 6
	s_mul_i32 s4, s4, 0xe0
	s_add_i32 s4, s4, s2
	s_addk_i32 s4, 0xffe0
	s_cmpk_gt_i32 s4, 0x47f
	s_cbranch_scc1 .Lhp_done
	s_load_dwordx2 s[12:13], s[0:1], 0x130
	s_and_b32 s5, s4, 3
	s_lshl_b32 s6, 1, s5
	s_lshr_b32 s7, s4, 2
	s_cmpk_lt_u32 s7, 32
	s_cbranch_scc0 .Lhp_lat
	s_lshr_b32 s8, s7, 3
	s_lshl_b32 s8, s8, 8
	s_and_b32 s10, s7, 7
	s_movk_i32 s9, 0x100
	s_branch .Lhp_dec
.Lhp_lat:
	s_sub_i32 s7, s7, 32
	s_lshr_b32 s8, s7, 6
	s_lshl_b32 s8, s8, 11
	s_addk_i32 s8, 0x400
	s_and_b32 s10, s7, 63
	s_movk_i32 s9, 0x800
.Lhp_dec:
	s_lshl_b32 s10, s10, 5
	v_and_b32_e32 v1, 63, v0
	v_lshrrev_b32_e32 v4, 4, v1
	v_lshl_add_u32 v4, v4, 3, s10
	v_and_b32_e32 v5, 15, v1
	v_lshlrev_b32_e32 v5, 4, v5
	v_lshl_add_u32 v5, s5, 8, v5
	s_waitcnt lgkmcnt(0)
	s_mul_i32 s11, s8, 0x6000
	s_add_u32 s14, s12, 0x2a600000
	s_addc_u32 s15, s13, 0
	s_add_u32 s14, s14, s11
	s_addc_u32 s15, s15, 0
	s_lshl_b32 s11, s8, 10
	s_add_u32 s16, s12, 0x3c600000
	s_addc_u32 s17, s13, 0
	s_add_u32 s16, s16, s11
	s_addc_u32 s17, s17, 0
	v_mov_b32_e32 v10, 0
	v_mov_b32_e32 v11, 0
	v_mov_b32_e32 v12, 0
	v_mov_b32_e32 v13, 0
	v_mov_b32_e32 v14, 0
	v_mov_b32_e32 v15, 0
	v_mov_b32_e32 v16, 0
	v_mov_b32_e32 v17, 0
	v_mov_b32_e32 v18, 0
	v_mov_b32_e32 v19, 0
	v_mov_b32_e32 v20, 0
	v_mov_b32_e32 v21, 0
	v_mov_b32_e32 v22, 0
	v_mov_b32_e32 v23, 0
	v_mov_b32_e32 v24, 0
	v_mov_b32_e32 v25, 0
	v_mov_b32_e32 v26, 0
	v_mov_b32_e32 v27, 0
	v_mov_b32_e32 v28, 0
	v_mov_b32_e32 v29, 0
	v_mov_b32_e32 v30, 0
	v_mov_b32_e32 v31, 0
	v_mov_b32_e32 v32, 0
	v_mov_b32_e32 v33, 0
	v_mov_b32_e32 v34, 0
	v_mov_b32_e32 v35, 0
	v_mov_b32_e32 v36, 0
	v_mov_b32_e32 v37, 0
	v_mov_b32_e32 v38, 0
	v_mov_b32_e32 v39, 0
	v_mov_b32_e32 v40, 0
	v_mov_b32_e32 v41, 0
	v_mov_b32_e32 v42, 0
	v_mov_b32_e32 v43, 0
	v_mov_b32_e32 v44, 0
	v_mov_b32_e32 v45, 0
	v_mov_b32_e32 v46, 0
	v_mov_b32_e32 v47, 0
	v_mov_b32_e32 v48, 0
	v_mov_b32_e32 v49, 0
	v_mov_b32_e32 v50, 0
	v_mov_b32_e32 v51, 0
	v_mov_b32_e32 v52, 0
	v_mov_b32_e32 v53, 0
	v_mov_b32_e32 v54, 0
	v_mov_b32_e32 v55, 0
	v_mov_b32_e32 v56, 0
	v_mov_b32_e32 v57, 0
	v_mov_b32_e32 v58, 0
	v_mov_b32_e32 v59, 0
	v_mov_b32_e32 v60, 0
	v_mov_b32_e32 v61, 0
	v_mov_b32_e32 v62, 0
	v_mov_b32_e32 v63, 0
	v_mov_b32_e32 v64, 0
	v_mov_b32_e32 v65, 0
	v_mov_b32_e32 v66, 0
	v_mov_b32_e32 v67, 0
	v_mov_b32_e32 v68, 0
	v_mov_b32_e32 v69, 0
	v_mov_b32_e32 v70, 0
	v_mov_b32_e32 v71, 0
	v_mov_b32_e32 v72, 0
	v_mov_b32_e32 v73, 0
	v_mov_b32_e32 v74, 0
	v_mov_b32_e32 v75, 0
	v_mov_b32_e32 v76, 0
	v_mov_b32_e32 v77, 0
	v_mov_b32_e32 v78, 0
	v_mov_b32_e32 v79, 0
	v_mov_b32_e32 v80, 0
	v_mov_b32_e32 v81, 0
	v_mov_b32_e32 v82, 0
	v_mov_b32_e32 v83, 0
	v_mov_b32_e32 v84, 0
	v_mov_b32_e32 v85, 0
	v_mov_b32_e32 v86, 0
	v_mov_b32_e32 v87, 0
	v_mov_b32_e32 v88, 0
	v_mov_b32_e32 v89, 0
	v_mov_b32_e32 v90, 0
	v_mov_b32_e32 v91, 0
	v_mov_b32_e32 v92, 0
	v_mov_b32_e32 v93, 0
	v_mov_b32_e32 v94, 0
	v_mov_b32_e32 v95, 0
	v_mov_b32_e32 v96, 0
	v_mov_b32_e32 v97, 0
	v_mov_b32_e32 v98, 0
	v_mov_b32_e32 v99, 0
	v_mov_b32_e32 v100, 0
	v_mov_b32_e32 v101, 0
	v_mov_b32_e32 v102, 0
	v_mov_b32_e32 v103, 0
	v_mov_b32_e32 v104, 0
	v_mov_b32_e32 v105, 0
	v_mov_b32_e32 v106, 0
	v_mov_b32_e32 v107, 0
	v_mov_b32_e32 v108, 0
	v_mov_b32_e32 v109, 0
	v_mov_b32_e32 v110, 0
	v_mov_b32_e32 v111, 0
	v_mov_b32_e32 v112, 0
	v_mov_b32_e32 v113, 0
	v_mov_b32_e32 v114, 0
	v_mov_b32_e32 v115, 0
	v_mov_b32_e32 v116, 0
	v_mov_b32_e32 v117, 0
	v_mov_b32_e32 v118, 0
	v_mov_b32_e32 v119, 0
	v_mov_b32_e32 v120, 0
	v_mov_b32_e32 v121, 0
	v_mov_b32_e32 v122, 0
	v_mov_b32_e32 v123, 0
	v_mov_b32_e32 v124, 0
	v_mov_b32_e32 v125, 0
	v_mov_b32_e32 v126, 0
	v_mov_b32_e32 v127, 0
	v_mov_b32_e32 v128, 0
	v_mov_b32_e32 v129, 0
	v_mov_b32_e32 v130, 0
	v_mov_b32_e32 v131, 0
	v_mov_b32_e32 v132, 0
	v_mov_b32_e32 v133, 0
	v_mov_b32_e32 v134, 0
	v_mov_b32_e32 v135, 0
	v_mov_b32_e32 v136, 0
	v_mov_b32_e32 v137, 0
	v_mov_b32_e32 v138, 0
	v_mov_b32_e32 v139, 0
	v_mov_b32_e32 v140, 0
	v_mov_b32_e32 v141, 0
	v_mov_b32_e32 v142, 0
	v_mov_b32_e32 v143, 0
	v_mov_b32_e32 v144, 0
	v_mov_b32_e32 v145, 0
	v_mov_b32_e32 v146, 0
	v_mov_b32_e32 v147, 0
	v_mov_b32_e32 v148, 0
	v_mov_b32_e32 v149, 0
	v_mov_b32_e32 v150, 0
	v_mov_b32_e32 v151, 0
	v_mov_b32_e32 v152, 0
	v_mov_b32_e32 v153, 0
	v_mov_b32_e32 v154, 0
	v_mov_b32_e32 v155, 0
	v_mov_b32_e32 v156, 0
	v_mov_b32_e32 v157, 0
	v_mov_b32_e32 v158, 0
	v_mov_b32_e32 v159, 0
	v_mov_b32_e32 v160, 0
	v_mov_b32_e32 v161, 0
	v_mov_b32_e32 v162, 0
	v_mov_b32_e32 v163, 0
	v_mov_b32_e32 v164, 0
	v_mov_b32_e32 v165, 0
	s_movk_i32 s22, 0x6000
	s_cmp_eq_u32 s5, 0
	s_cbranch_scc1 .Lhp_w0
	s_cmp_eq_u32 s5, 1
	s_cbranch_scc1 .Lhp_w1
	s_cmp_eq_u32 s5, 2
	s_cbranch_scc1 .Lhp_w2
; #define GAS __attribute__((address_space(1)))
; __device__ __forceinline__ void prep_phase(Frame& F, CArgs a, int l, unsigned long long& tm_acc) {
;     ...
;             auto body = [&](auto WC) { constexpr int W = decltype(WC)::value;
;                 u32x4 v[W]; float mk[W];
; #pragma unroll
;                 for (int j = 0; j < W; ++j) { const int tt = t - W / 2 + j; const bool ok = tt >= 0 && tt < L; mk[j] = ok ? 1.f : 0.f; cnt += ok ? 1 : 0; v[j] = *(const GAS u32x4*)(zc + (size_t)(ok ? tt : t) * DIN); }
; #pragma unroll
;                 for (int j = 0; j < W; ++j) { s[0] += mk[j] * bflo(v[j].x); s[1] += mk[j] * bfhi(v[j].x); s[2] += mk[j] * bflo(v[j].y); s[3] += mk[j] * bfhi(v[j].y);
;                     s[4] += mk[j] * bflo(v[j].z); s[5] += mk[j] * bfhi(v[j].z); s[6] += mk[j] * bflo(v[j].w); s[7] += mk[j] * bfhi(v[j].w); } };
.Lhp_w3:
	v_add_u32_e32 v3, -8, v4
	v_mul_lo_u32 v2, v3, s22
	v_add_u32_e32 v2, v2, v5
	v_cmp_gt_u32_e64 s[18:19], s9, v3
	s_nop 1
	s_mov_b64 exec, s[18:19]
	global_load_dwordx4 v[10:13], v2, s[14:15]
	s_mov_b64 exec, -1
	v_add_u32_e32 v3, 1, v3
	v_add_u32_e32 v2, s22, v2
	v_cmp_gt_u32_e64 s[18:19], s9, v3
	s_nop 1
	s_mov_b64 exec, s[18:19]
	global_load_dwordx4 v[14:17], v2, s[14:15]
	s_mov_b64 exec, -1
	v_add_u32_e32 v3, 1, v3
	v_add_u32_e32 v2, s22, v2
	v_cmp_gt_u32_e64 s[18:19], s9, v3
	s_nop 1
	s_mov_b64 exec, s[18:19]
	global_load_dwordx4 v[18:21], v2, s[14:15]
	s_mov_b64 exec, -1
	v_add_u32_e32 v3, 1, v3
	v_add_u32_e32 v2, s22, v2
	v_cmp_gt_u32_e64 s[18:19], s9, v3
	s_nop 1
	s_mov_b64 exec, s[18:19]
	global_load_dwordx4 v[22:25], v2, s[14:15]
	s_mov_b64 exec, -1
	v_add_u32_e32 v3, 1, v3
	v_add_u32_e32 v2, s22, v2
	v_cmp_gt_u32_e64 s[18:19], s9, v3
	s_nop 1
	s_mov_b64 exec, s[18:19]
	global_load_dwordx4 v[26:29], v2, s[14:15]
	s_mov_b64 exec, -1
	v_add_u32_e32 v3, 1, v3
	v_add_u32_e32 v2, s22, v2
	v_cmp_gt_u32_e64 s[18:19], s9, v3
	s_nop 1
	s_mov_b64 exec, s[18:19]
	global_load_dwordx4 v[30:33], v2, s[14:15]
	s_mov_b64 exec, -1
	v_add_u32_e32 v3, 1, v3
	v_add_u32_e32 v2, s22, v2
	v_cmp_gt_u32_e64 s[18:19], s9, v3
	s_nop 1
	s_mov_b64 exec, s[18:19]
	global_load_dwordx4 v[34:37], v2, s[14:15]
	s_mov_b64 exec, -1
	v_add_u32_e32 v3, 1, v3
	v_add_u32_e32 v2, s22, v2
	v_cmp_gt_u32_e64 s[18:19], s9, v3
	s_nop 1
	s_mov_b64 exec, s[18:19]
	global_load_dwordx4 v[38:41], v2, s[14:15]
	s_mov_b64 exec, -1
	v_add_u32_e32 v3, 1, v3
	v_add_u32_e32 v2, s22, v2
	v_cmp_gt_u32_e64 s[18:19], s9, v3
	s_nop 1
	s_mov_b64 exec, s[18:19]
	global_load_dwordx4 v[42:45], v2, s[14:15]
	s_mov_b64 exec, -1
	v_add_u32_e32 v3, 1, v3
	v_add_u32_e32 v2, s22, v2
	v_cmp_gt_u32_e64 s[18:19], s9, v3
	s_nop 1
	s_mov_b64 exec, s[18:19]
	global_load_dwordx4 v[46:49], v2, s[14:15]
	s_mov_b64 exec, -1
	v_add_u32_e32 v3, 1, v3
	v_add_u32_e32 v2, s22, v2
	v_cmp_gt_u32_e64 s[18:19], s9, v3
	s_nop 1
	s_mov_b64 exec, s[18:19]
	global_load_dwordx4 v[50:53], v2, s[14:15]
	s_mov_b64 exec, -1
	v_add_u32_e32 v3, 1, v3
	v_add_u32_e32 v2, s22, v2
	v_cmp_gt_u32_e64 s[18:19], s9, v3
	s_nop 1
	s_mov_b64 exec, s[18:19]
	global_load_dwordx4 v[54:57], v2, s[14:15]
	s_mov_b64 exec, -1
	v_add_u32_e32 v3, 1, v3
	v_add_u32_e32 v2, s22, v2
	v_cmp_gt_u32_e64 s[18:19], s9, v3
	s_nop 1
	s_mov_b64 exec, s[18:19]
	global_load_dwordx4 v[58:61], v2, s[14:15]
	s_mov_b64 exec, -1
	v_add_u32_e32 v3, 1, v3
	v_add_u32_e32 v2, s22, v2
	v_cmp_gt_u32_e64 s[18:19], s9, v3
	s_nop 1
	s_mov_b64 exec, s[18:19]
	global_load_dwordx4 v[62:65], v2, s[14:15]
	s_mov_b64 exec, -1
	v_add_u32_e32 v3, 1, v3
	v_add_u32_e32 v2, s22, v2
	v_cmp_gt_u32_e64 s[18:19], s9, v3
	s_nop 1
	s_mov_b64 exec, s[18:19]
	global_load_dwordx4 v[66:69], v2, s[14:15]
	s_mov_b64 exec, -1
	v_add_u32_e32 v3, 1, v3
	v_add_u32_e32 v2, s22, v2
	v_cmp_gt_u32_e64 s[18:19], s9, v3
	s_nop 1
	s_mov_b64 exec, s[18:19]
	global_load_dwordx4 v[70:73], v2, s[14:15]
	s_mov_b64 exec, -1
	v_add_u32_e32 v3, 1, v3
	v_add_u32_e32 v2, s22, v2
	v_cmp_gt_u32_e64 s[18:19], s9, v3
	s_nop 1
	s_mov_b64 exec, s[18:19]
	global_load_dwordx4 v[74:77], v2, s[14:15]
	s_mov_b64 exec, -1
	v_add_u32_e32 v3, 1, v3
	v_add_u32_e32 v2, s22, v2
	v_cmp_gt_u32_e64 s[18:19], s9, v3
	s_nop 1
	s_mov_b64 exec, s[18:19]
	global_load_dwordx4 v[78:81], v2, s[14:15]
	s_mov_b64 exec, -1
	v_add_u32_e32 v3, 1, v3
	v_add_u32_e32 v2, s22, v2
	v_cmp_gt_u32_e64 s[18:19], s9, v3
	s_nop 1
	s_mov_b64 exec, s[18:19]
	global_load_dwordx4 v[82:85], v2, s[14:15]
	s_mov_b64 exec, -1
	v_add_u32_e32 v3, 1, v3
	v_add_u32_e32 v2, s22, v2
	v_cmp_gt_u32_e64 s[18:19], s9, v3
	s_nop 1
	s_mov_b64 exec, s[18:19]
	global_load_dwordx4 v[86:89], v2, s[14:15]
	s_mov_b64 exec, -1
	v_add_u32_e32 v3, 1, v3
	v_add_u32_e32 v2, s22, v2
	v_cmp_gt_u32_e64 s[18:19], s9, v3
	s_nop 1
	s_mov_b64 exec, s[18:19]
	global_load_dwordx4 v[90:93], v2, s[14:15]
	s_mov_b64 exec, -1
	v_add_u32_e32 v3, 1, v3
	v_add_u32_e32 v2, s22, v2
	v_cmp_gt_u32_e64 s[18:19], s9, v3
	s_nop 1
	s_mov_b64 exec, s[18:19]
	global_load_dwordx4 v[94:97], v2, s[14:15]
	s_mov_b64 exec, -1
	v_add_u32_e32 v3, 1, v3
	v_add_u32_e32 v2, s22, v2
	v_cmp_gt_u32_e64 s[18:19], s9, v3
	s_nop 1
	s_mov_b64 exec, s[18:19]
	global_load_dwordx4 v[98:101], v2, s[14:15]
	s_mov_b64 exec, -1
	s_waitcnt vmcnt(0)
; #define GAS __attribute__((address_space(1)))
; __device__ __forceinline__ void prep_phase(Frame& F, CArgs a, int l, unsigned long long& tm_acc) {
;     ...
;             auto body = [&](auto WC) { constexpr int W = decltype(WC)::value;
;                 u32x4 v[W]; float mk[W];
; #pragma unroll
;                 for (int j = 0; j < W; ++j) { const int tt = t - W / 2 + j; const bool ok = tt >= 0 && tt < L; mk[j] = ok ? 1.f : 0.f; cnt += ok ? 1 : 0; v[j] = *(const GAS u32x4*)(zc + (size_t)(ok ? tt : t) * DIN); }
; #pragma unroll
;                 for (int j = 0; j < W; ++j) { s[0] += mk[j] * bflo(v[j].x); s[1] += mk[j] * bfhi(v[j].x); s[2] += mk[j] * bflo(v[j].y); s[3] += mk[j] * bfhi(v[j].y);
;                     s[4] += mk[j] * bflo(v[j].z); s[5] += mk[j] * bfhi(v[j].z); s[6] += mk[j] * bflo(v[j].w); s[7] += mk[j] * bfhi(v[j].w); } };
	v_lshlrev_b32_e32 v166, 16, v10
	v_and_b32_e32 v167, 0xffff0000, v10
	v_lshlrev_b32_e32 v168, 16, v11
	v_and_b32_e32 v169, 0xffff0000, v11
	v_lshlrev_b32_e32 v170, 16, v12
	v_and_b32_e32 v171, 0xffff0000, v12
	v_lshlrev_b32_e32 v172, 16, v13
	v_and_b32_e32 v173, 0xffff0000, v13
	v_pk_add_f32 v[102:103], v[102:103], v[166:167]
	v_pk_add_f32 v[104:105], v[104:105], v[168:169]
	v_pk_add_f32 v[106:107], v[106:107], v[170:171]
	v_pk_add_f32 v[108:109], v[108:109], v[172:173]
	v_lshlrev_b32_e32 v166, 16, v14
	v_and_b32_e32 v167, 0xffff0000, v14
	v_lshlrev_b32_e32 v168, 16, v15
	v_and_b32_e32 v169, 0xffff0000, v15
	v_lshlrev_b32_e32 v170, 16, v16
	v_and_b32_e32 v171, 0xffff0000, v16
	v_lshlrev_b32_e32 v172, 16, v17
	v_and_b32_e32 v173, 0xffff0000, v17
	v_pk_add_f32 v[102:103], v[102:103], v[166:167]
	v_pk_add_f32 v[104:105], v[104:105], v[168:169]
	v_pk_add_f32 v[106:107], v[106:107], v[170:171]
	v_pk_add_f32 v[108:109], v[108:109], v[172:173]
	v_pk_add_f32 v[110:111], v[110:111], v[166:167]
	v_pk_add_f32 v[112:113], v[112:113], v[168:169]
	v_pk_add_f32 v[114:115], v[114:115], v[170:171]
	v_pk_add_f32 v[116:117], v[116:117], v[172:173]
	v_lshlrev_b32_e32 v166, 16, v18
	v_and_b32_e32 v167, 0xffff0000, v18
	v_lshlrev_b32_e32 v168, 16, v19
	v_and_b32_e32 v169, 0xffff0000, v19
	v_lshlrev_b32_e32 v170, 16, v20
	v_and_b32_e32 v171, 0xffff0000, v20
	v_lshlrev_b32_e32 v172, 16, v21
	v_and_b32_e32 v173, 0xffff0000, v21
	v_pk_add_f32 v[102:103], v[102:103], v[166:167]
	v_pk_add_f32 v[104:105], v[104:105], v[168:169]
	v_pk_add_f32 v[106:107], v[106:107], v[170:171]
	v_pk_add_f32 v[108:109], v[108:109], v[172:173]
	v_pk_add_f32 v[110:111], v[110:111], v[166:167]
	v_pk_add_f32 v[112:113], v[112:113], v[168:169]
	v_pk_add_f32 v[114:115], v[114:115], v[170:171]
	v_pk_add_f32 v[116:117], v[116:117], v[172:173]
	v_pk_add_f32 v[118:119], v[118:119], v[166:167]
	v_pk_add_f32 v[120:121], v[120:121], v[168:169]
	v_pk_add_f32 v[122:123], v[122:123], v[170:171]
	v_pk_add_f32 v[124:125], v[124:125], v[172:173]
	v_lshlrev_b32_e32 v166, 16, v22
	v_and_b32_e32 v167, 0xffff0000, v22
	v_lshlrev_b32_e32 v168, 16, v23
	v_and_b32_e32 v169, 0xffff0000, v23
	v_lshlrev_b32_e32 v170, 16, v24
	v_and_b32_e32 v171, 0xffff0000, v24
	v_lshlrev_b32_e32 v172, 16, v25
	v_and_b32_e32 v173, 0xffff0000, v25
	v_pk_add_f32 v[102:103], v[102:103], v[166:167]
	v_pk_add_f32 v[104:105], v[104:105], v[168:169]
	v_pk_add_f32 v[106:107], v[106:107], v[170:171]
	v_pk_add_f32 v[108:109], v[108:109], v[172:173]
	v_pk_add_f32 v[110:111], v[110:111], v[166:167]
	v_pk_add_f32 v[112:113], v[112:113], v[168:169]
	v_pk_add_f32 v[114:115], v[114:115], v[170:171]
	v_pk_add_f32 v[116:117], v[116:117], v[172:173]
	v_pk_add_f32 v[118:119], v[118:119], v[166:167]
	v_pk_add_f32 v[120:121], v[120:121], v[168:169]
	v_pk_add_f32 v[122:123], v[122:123], v[170:171]
	v_pk_add_f32 v[124:125], v[124:125], v[172:173]
	v_pk_add_f32 v[126:127], v[126:127], v[166:167]
	v_pk_add_f32 v[128:129], v[128:129], v[168:169]
	v_pk_add_f32 v[130:131], v[130:131], v[170:171]
	v_pk_add_f32 v[132:133], v[132:133], v[172:173]
	v_lshlrev_b32_e32 v166, 16, v26
	v_and_b32_e32 v167, 0xffff0000, v26
	v_lshlrev_b32_e32 v168, 16, v27
	v_and_b32_e32 v169, 0xffff0000, v27
	v_lshlrev_b32_e32 v170, 16, v28
	v_and_b32_e32 v171, 0xffff0000, v28
	v_lshlrev_b32_e32 v172, 16, v29
	v_and_b32_e32 v173, 0xffff0000, v29
	v_pk_add_f32 v[102:103], v[102:103], v[166:167]
	v_pk_add_f32 v[104:105], v[104:105], v[168:169]
	v_pk_add_f32 v[106:107], v[106:107], v[170:171]
	v_pk_add_f32 v[108:109], v[108:109], v[172:173]
	v_pk_add_f32 v[110:111], v[110:111], v[166:167]
	v_pk_add_f32 v[112:113], v[112:113], v[168:169]
	v_pk_add_f32 v[114:115], v[114:115], v[170:171]
	v_pk_add_f32 v[116:117], v[116:117], v[172:173]
	v_pk_add_f32 v[118:119], v[118:119], v[166:167]
	v_pk_add_f32 v[120:121], v[120:121], v[168:169]
	v_pk_add_f32 v[122:123], v[122:123], v[170:171]
	v_pk_add_f32 v[124:125], v[124:125], v[172:173]
	v_pk_add_f32 v[126:127], v[126:127], v[166:167]
	v_pk_add_f32 v[128:129], v[128:129], v[168:169]
	v_pk_add_f32 v[130:131], v[130:131], v[170:171]
	v_pk_add_f32 v[132:133], v[132:133], v[172:173]
	v_pk_add_f32 v[134:135], v[134:135], v[166:167]
	v_pk_add_f32 v[136:137], v[136:137], v[168:169]
	v_pk_add_f32 v[138:139], v[138:139], v[170:171]
	v_pk_add_f32 v[140:141], v[140:141], v[172:173]
	v_lshlrev_b32_e32 v166, 16, v30
	v_and_b32_e32 v167, 0xffff0000, v30
	v_lshlrev_b32_e32 v168, 16, v31
	v_and_b32_e32 v169, 0xffff0000, v31
	v_lshlrev_b32_e32 v170, 16, v32
	v_and_b32_e32 v171, 0xffff0000, v32
	v_lshlrev_b32_e32 v172, 16, v33
	v_and_b32_e32 v173, 0xffff0000, v33
	v_pk_add_f32 v[102:103], v[102:103], v[166:167]
	v_pk_add_f32 v[104:105], v[104:105], v[168:169]
	v_pk_add_f32 v[106:107], v[106:107], v[170:171]
	v_pk_add_f32 v[108:109], v[108:109], v[172:173]
	v_pk_add_f32 v[110:111], v[110:111], v[166:167]
	v_pk_add_f32 v[112:113], v[112:113], v[168:169]
	v_pk_add_f32 v[114:115], v[114:115], v[170:171]
	v_pk_add_f32 v[116:117], v[116:117], v[172:173]
	v_pk_add_f32 v[118:119], v[118:119], v[166:167]
	v_pk_add_f32 v[120:121], v[120:121], v[168:169]
	v_pk_add_f32 v[122:123], v[122:123], v[170:171]
	v_pk_add_f32 v[124:125], v[124:125], v[172:173]
	v_pk_add_f32 v[126:127], v[126:127], v[166:167]
	v_pk_add_f32 v[128:129], v[128:129], v[168:169]
	v_pk_add_f32 v[130:131], v[130:131], v[170:171]
	v_pk_add_f32 v[132:133], v[132:133], v[172:173]
	v_pk_add_f32 v[134:135], v[134:135], v[166:167]
	v_pk_add_f32 v[136:137], v[136:137], v[168:169]
	v_pk_add_f32 v[138:139], v[138:139], v[170:171]
	v_pk_add_f32 v[140:141], v[140:141], v[172:173]
	v_pk_add_f32 v[142:143], v[142:143], v[166:167]
; #define GAS __attribute__((address_space(1)))
; __device__ __forceinline__ void prep_phase(Frame& F, CArgs a, int l, unsigned long long& tm_acc) {
;     ...
;             auto body = [&](auto WC) { constexpr int W = decltype(WC)::value;
;                 u32x4 v[W]; float mk[W];
; #pragma unroll
;                 for (int j = 0; j < W; ++j) { const int tt = t - W / 2 + j; const bool ok = tt >= 0 && tt < L; mk[j] = ok ? 1.f : 0.f; cnt += ok ? 1 : 0; v[j] = *(const GAS u32x4*)(zc + (size_t)(ok ? tt : t) * DIN); }
; #pragma unroll
;                 for (int j = 0; j < W; ++j) { s[0] += mk[j] * bflo(v[j].x); s[1] += mk[j] * bfhi(v[j].x); s[2] += mk[j] * bflo(v[j].y); s[3] += mk[j] * bfhi(v[j].y);
;                     s[4] += mk[j] * bflo(v[j].z); s[5] += mk[j] * bfhi(v[j].z); s[6] += mk[j] * bflo(v[j].w); s[7] += mk[j] * bfhi(v[j].w); } };
	v_pk_add_f32 v[144:145], v[144:145], v[168:169]
	v_pk_add_f32 v[146:147], v[146:147], v[170:171]
	v_pk_add_f32 v[148:149], v[148:149], v[172:173]
	v_lshlrev_b32_e32 v166, 16, v34
	v_and_b32_e32 v167, 0xffff0000, v34
	v_lshlrev_b32_e32 v168, 16, v35
	v_and_b32_e32 v169, 0xffff0000, v35
	v_lshlrev_b32_e32 v170, 16, v36
	v_and_b32_e32 v171, 0xffff0000, v36
	v_lshlrev_b32_e32 v172, 16, v37
	v_and_b32_e32 v173, 0xffff0000, v37
	v_pk_add_f32 v[102:103], v[102:103], v[166:167]
	v_pk_add_f32 v[104:105], v[104:105], v[168:169]
	v_pk_add_f32 v[106:107], v[106:107], v[170:171]
	v_pk_add_f32 v[108:109], v[108:109], v[172:173]
	v_pk_add_f32 v[110:111], v[110:111], v[166:167]
	v_pk_add_f32 v[112:113], v[112:113], v[168:169]
	v_pk_add_f32 v[114:115], v[114:115], v[170:171]
	v_pk_add_f32 v[116:117], v[116:117], v[172:173]
	v_pk_add_f32 v[118:119], v[118:119], v[166:167]
	v_pk_add_f32 v[120:121], v[120:121], v[168:169]
	v_pk_add_f32 v[122:123], v[122:123], v[170:171]
	v_pk_add_f32 v[124:125], v[124:125], v[172:173]
	v_pk_add_f32 v[126:127], v[126:127], v[166:167]
	v_pk_add_f32 v[128:129], v[128:129], v[168:169]
	v_pk_add_f32 v[130:131], v[130:131], v[170:171]
	v_pk_add_f32 v[132:133], v[132:133], v[172:173]
	v_pk_add_f32 v[134:135], v[134:135], v[166:167]
	v_pk_add_f32 v[136:137], v[136:137], v[168:169]
	v_pk_add_f32 v[138:139], v[138:139], v[170:171]
	v_pk_add_f32 v[140:141], v[140:141], v[172:173]
	v_pk_add_f32 v[142:143], v[142:143], v[166:167]
	v_pk_add_f32 v[144:145], v[144:145], v[168:169]
	v_pk_add_f32 v[146:147], v[146:147], v[170:171]
	v_pk_add_f32 v[148:149], v[148:149], v[172:173]
	v_pk_add_f32 v[150:151], v[150:151], v[166:167]
	v_pk_add_f32 v[152:153], v[152:153], v[168:169]
	v_pk_add_f32 v[154:155], v[154:155], v[170:171]
	v_pk_add_f32 v[156:157], v[156:157], v[172:173]
	v_lshlrev_b32_e32 v166, 16, v38
	v_and_b32_e32 v167, 0xffff0000, v38
	v_lshlrev_b32_e32 v168, 16, v39
	v_and_b32_e32 v169, 0xffff0000, v39
	v_lshlrev_b32_e32 v170, 16, v40
	v_and_b32_e32 v171, 0xffff0000, v40
	v_lshlrev_b32_e32 v172, 16, v41
	v_and_b32_e32 v173, 0xffff0000, v41
	v_pk_add_f32 v[102:103], v[102:103], v[166:167]
	v_pk_add_f32 v[104:105], v[104:105], v[168:169]
	v_pk_add_f32 v[106:107], v[106:107], v[170:171]
	v_pk_add_f32 v[108:109], v[108:109], v[172:173]
	v_pk_add_f32 v[110:111], v[110:111], v[166:167]
	v_pk_add_f32 v[112:113], v[112:113], v[168:169]
	v_pk_add_f32 v[114:115], v[114:115], v[170:171]
	v_pk_add_f32 v[116:117], v[116:117], v[172:173]
	v_pk_add_f32 v[118:119], v[118:119], v[166:167]
	v_pk_add_f32 v[120:121], v[120:121], v[168:169]
	v_pk_add_f32 v[122:123], v[122:123], v[170:171]
	v_pk_add_f32 v[124:125], v[124:125], v[172:173]
	v_pk_add_f32 v[126:127], v[126:127], v[166:167]
	v_pk_add_f32 v[128:129], v[128:129], v[168:169]
	v_pk_add_f32 v[130:131], v[130:131], v[170:171]
	v_pk_add_f32 v[132:133], v[132:133], v[172:173]
	v_pk_add_f32 v[134:135], v[134:135], v[166:167]
	v_pk_add_f32 v[136:137], v[136:137], v[168:169]
	v_pk_add_f32 v[138:139], v[138:139], v[170:171]
	v_pk_add_f32 v[140:141], v[140:141], v[172:173]
	v_pk_add_f32 v[142:143], v[142:143], v[166:167]
	v_pk_add_f32 v[144:145], v[144:145], v[168:169]
	v_pk_add_f32 v[146:147], v[146:147], v[170:171]
	v_pk_add_f32 v[148:149], v[148:149], v[172:173]
	v_pk_add_f32 v[150:151], v[150:151], v[166:167]
	v_pk_add_f32 v[152:153], v[152:153], v[168:169]
	v_pk_add_f32 v[154:155], v[154:155], v[170:171]
	v_pk_add_f32 v[156:157], v[156:157], v[172:173]
	v_pk_add_f32 v[158:159], v[158:159], v[166:167]
	v_pk_add_f32 v[160:161], v[160:161], v[168:169]
	v_pk_add_f32 v[162:163], v[162:163], v[170:171]
	v_pk_add_f32 v[164:165], v[164:165], v[172:173]
	v_lshlrev_b32_e32 v166, 16, v42
	v_and_b32_e32 v167, 0xffff0000, v42
	v_lshlrev_b32_e32 v168, 16, v43
	v_and_b32_e32 v169, 0xffff0000, v43
	v_lshlrev_b32_e32 v170, 16, v44
	v_and_b32_e32 v171, 0xffff0000, v44
	v_lshlrev_b32_e32 v172, 16, v45
	v_and_b32_e32 v173, 0xffff0000, v45
	v_pk_add_f32 v[102:103], v[102:103], v[166:167]
	v_pk_add_f32 v[104:105], v[104:105], v[168:169]
	v_pk_add_f32 v[106:107], v[106:107], v[170:171]
	v_pk_add_f32 v[108:109], v[108:109], v[172:173]
	v_pk_add_f32 v[110:111], v[110:111], v[166:167]
	v_pk_add_f32 v[112:113], v[112:113], v[168:169]
	v_pk_add_f32 v[114:115], v[114:115], v[170:171]
	v_pk_add_f32 v[116:117], v[116:117], v[172:173]
	v_pk_add_f32 v[118:119], v[118:119], v[166:167]
	v_pk_add_f32 v[120:121], v[120:121], v[168:169]
	v_pk_add_f32 v[122:123], v[122:123], v[170:171]
	v_pk_add_f32 v[124:125], v[124:125], v[172:173]
	v_pk_add_f32 v[126:127], v[126:127], v[166:167]
	v_pk_add_f32 v[128:129], v[128:129], v[168:169]
	v_pk_add_f32 v[130:131], v[130:131], v[170:171]
	v_pk_add_f32 v[132:133], v[132:133], v[172:173]
	v_pk_add_f32 v[134:135], v[134:135], v[166:167]
	v_pk_add_f32 v[136:137], v[136:137], v[168:169]
	v_pk_add_f32 v[138:139], v[138:139], v[170:171]
	v_pk_add_f32 v[140:141], v[140:141], v[172:173]
	v_pk_add_f32 v[142:143], v[142:143], v[166:167]
	v_pk_add_f32 v[144:145], v[144:145], v[168:169]
	v_pk_add_f32 v[146:147], v[146:147], v[170:171]
	v_pk_add_f32 v[148:149], v[148:149], v[172:173]
	v_pk_add_f32 v[150:151], v[150:151], v[166:167]
	v_pk_add_f32 v[152:153], v[152:153], v[168:169]
	v_pk_add_f32 v[154:155], v[154:155], v[170:171]
	v_pk_add_f32 v[156:157], v[156:157], v[172:173]
	v_pk_add_f32 v[158:159], v[158:159], v[166:167]
	v_pk_add_f32 v[160:161], v[160:161], v[168:169]
	v_pk_add_f32 v[162:163], v[162:163], v[170:171]
	v_pk_add_f32 v[164:165], v[164:165], v[172:173]
	v_lshlrev_b32_e32 v166, 16, v46
	v_and_b32_e32 v167, 0xffff0000, v46
	v_lshlrev_b32_e32 v168, 16, v47
	v_and_b32_e32 v169, 0xffff0000, v47
; #define GAS __attribute__((address_space(1)))
; __device__ __forceinline__ void prep_phase(Frame& F, CArgs a, int l, unsigned long long& tm_acc) {
;     ...
;             auto body = [&](auto WC) { constexpr int W = decltype(WC)::value;
;                 u32x4 v[W]; float mk[W];
; #pragma unroll
;                 for (int j = 0; j < W; ++j) { const int tt = t - W / 2 + j; const bool ok = tt >= 0 && tt < L; mk[j] = ok ? 1.f : 0.f; cnt += ok ? 1 : 0; v[j] = *(const GAS u32x4*)(zc + (size_t)(ok ? tt : t) * DIN); }
; #pragma unroll
;                 for (int j = 0; j < W; ++j) { s[0] += mk[j] * bflo(v[j].x); s[1] += mk[j] * bfhi(v[j].x); s[2] += mk[j] * bflo(v[j].y); s[3] += mk[j] * bfhi(v[j].y);
;                     s[4] += mk[j] * bflo(v[j].z); s[5] += mk[j] * bfhi(v[j].z); s[6] += mk[j] * bflo(v[j].w); s[7] += mk[j] * bfhi(v[j].w); } };
	v_lshlrev_b32_e32 v170, 16, v48
	v_and_b32_e32 v171, 0xffff0000, v48
	v_lshlrev_b32_e32 v172, 16, v49
	v_and_b32_e32 v173, 0xffff0000, v49
	v_pk_add_f32 v[102:103], v[102:103], v[166:167]
	v_pk_add_f32 v[104:105], v[104:105], v[168:169]
	v_pk_add_f32 v[106:107], v[106:107], v[170:171]
	v_pk_add_f32 v[108:109], v[108:109], v[172:173]
	v_pk_add_f32 v[110:111], v[110:111], v[166:167]
	v_pk_add_f32 v[112:113], v[112:113], v[168:169]
	v_pk_add_f32 v[114:115], v[114:115], v[170:171]
	v_pk_add_f32 v[116:117], v[116:117], v[172:173]
	v_pk_add_f32 v[118:119], v[118:119], v[166:167]
	v_pk_add_f32 v[120:121], v[120:121], v[168:169]
	v_pk_add_f32 v[122:123], v[122:123], v[170:171]
	v_pk_add_f32 v[124:125], v[124:125], v[172:173]
	v_pk_add_f32 v[126:127], v[126:127], v[166:167]
	v_pk_add_f32 v[128:129], v[128:129], v[168:169]
	v_pk_add_f32 v[130:131], v[130:131], v[170:171]
	v_pk_add_f32 v[132:133], v[132:133], v[172:173]
	v_pk_add_f32 v[134:135], v[134:135], v[166:167]
	v_pk_add_f32 v[136:137], v[136:137], v[168:169]
	v_pk_add_f32 v[138:139], v[138:139], v[170:171]
	v_pk_add_f32 v[140:141], v[140:141], v[172:173]
	v_pk_add_f32 v[142:143], v[142:143], v[166:167]
	v_pk_add_f32 v[144:145], v[144:145], v[168:169]
	v_pk_add_f32 v[146:147], v[146:147], v[170:171]
	v_pk_add_f32 v[148:149], v[148:149], v[172:173]
	v_pk_add_f32 v[150:151], v[150:151], v[166:167]
	v_pk_add_f32 v[152:153], v[152:153], v[168:169]
	v_pk_add_f32 v[154:155], v[154:155], v[170:171]
	v_pk_add_f32 v[156:157], v[156:157], v[172:173]
	v_pk_add_f32 v[158:159], v[158:159], v[166:167]
	v_pk_add_f32 v[160:161], v[160:161], v[168:169]
	v_pk_add_f32 v[162:163], v[162:163], v[170:171]
	v_pk_add_f32 v[164:165], v[164:165], v[172:173]
	v_lshlrev_b32_e32 v166, 16, v50
	v_and_b32_e32 v167, 0xffff0000, v50
	v_lshlrev_b32_e32 v168, 16, v51
	v_and_b32_e32 v169, 0xffff0000, v51
	v_lshlrev_b32_e32 v170, 16, v52
	v_and_b32_e32 v171, 0xffff0000, v52
	v_lshlrev_b32_e32 v172, 16, v53
	v_and_b32_e32 v173, 0xffff0000, v53
	v_pk_add_f32 v[102:103], v[102:103], v[166:167]
	v_pk_add_f32 v[104:105], v[104:105], v[168:169]
	v_pk_add_f32 v[106:107], v[106:107], v[170:171]
	v_pk_add_f32 v[108:109], v[108:109], v[172:173]
	v_pk_add_f32 v[110:111], v[110:111], v[166:167]
	v_pk_add_f32 v[112:113], v[112:113], v[168:169]
	v_pk_add_f32 v[114:115], v[114:115], v[170:171]
	v_pk_add_f32 v[116:117], v[116:117], v[172:173]
	v_pk_add_f32 v[118:119], v[118:119], v[166:167]
	v_pk_add_f32 v[120:121], v[120:121], v[168:169]
	v_pk_add_f32 v[122:123], v[122:123], v[170:171]
	v_pk_add_f32 v[124:125], v[124:125], v[172:173]
	v_pk_add_f32 v[126:127], v[126:127], v[166:167]
	v_pk_add_f32 v[128:129], v[128:129], v[168:169]
	v_pk_add_f32 v[130:131], v[130:131], v[170:171]
	v_pk_add_f32 v[132:133], v[132:133], v[172:173]
	v_pk_add_f32 v[134:135], v[134:135], v[166:167]
	v_pk_add_f32 v[136:137], v[136:137], v[168:169]
	v_pk_add_f32 v[138:139], v[138:139], v[170:171]
	v_pk_add_f32 v[140:141], v[140:141], v[172:173]
	v_pk_add_f32 v[142:143], v[142:143], v[166:167]
	v_pk_add_f32 v[144:145], v[144:145], v[168:169]
	v_pk_add_f32 v[146:147], v[146:147], v[170:171]
	v_pk_add_f32 v[148:149], v[148:149], v[172:173]
	v_pk_add_f32 v[150:151], v[150:151], v[166:167]
	v_pk_add_f32 v[152:153], v[152:153], v[168:169]
	v_pk_add_f32 v[154:155], v[154:155], v[170:171]
	v_pk_add_f32 v[156:157], v[156:157], v[172:173]
	v_pk_add_f32 v[158:159], v[158:159], v[166:167]
	v_pk_add_f32 v[160:161], v[160:161], v[168:169]
	v_pk_add_f32 v[162:163], v[162:163], v[170:171]
	v_pk_add_f32 v[164:165], v[164:165], v[172:173]
	v_lshlrev_b32_e32 v166, 16, v54
	v_and_b32_e32 v167, 0xffff0000, v54
	v_lshlrev_b32_e32 v168, 16, v55
	v_and_b32_e32 v169, 0xffff0000, v55
	v_lshlrev_b32_e32 v170, 16, v56
	v_and_b32_e32 v171, 0xffff0000, v56
	v_lshlrev_b32_e32 v172, 16, v57
	v_and_b32_e32 v173, 0xffff0000, v57
	v_pk_add_f32 v[102:103], v[102:103], v[166:167]
	v_pk_add_f32 v[104:105], v[104:105], v[168:169]
	v_pk_add_f32 v[106:107], v[106:107], v[170:171]
	v_pk_add_f32 v[108:109], v[108:109], v[172:173]
	v_pk_add_f32 v[110:111], v[110:111], v[166:167]
	v_pk_add_f32 v[112:113], v[112:113], v[168:169]
	v_pk_add_f32 v[114:115], v[114:115], v[170:171]
	v_pk_add_f32 v[116:117], v[116:117], v[172:173]
	v_pk_add_f32 v[118:119], v[118:119], v[166:167]
	v_pk_add_f32 v[120:121], v[120:121], v[168:169]
	v_pk_add_f32 v[122:123], v[122:123], v[170:171]
	v_pk_add_f32 v[124:125], v[124:125], v[172:173]
	v_pk_add_f32 v[126:127], v[126:127], v[166:167]
	v_pk_add_f32 v[128:129], v[128:129], v[168:169]
	v_pk_add_f32 v[130:131], v[130:131], v[170:171]
	v_pk_add_f32 v[132:133], v[132:133], v[172:173]
	v_pk_add_f32 v[134:135], v[134:135], v[166:167]
	v_pk_add_f32 v[136:137], v[136:137], v[168:169]
	v_pk_add_f32 v[138:139], v[138:139], v[170:171]
	v_pk_add_f32 v[140:141], v[140:141], v[172:173]
	v_pk_add_f32 v[142:143], v[142:143], v[166:167]
	v_pk_add_f32 v[144:145], v[144:145], v[168:169]
	v_pk_add_f32 v[146:147], v[146:147], v[170:171]
	v_pk_add_f32 v[148:149], v[148:149], v[172:173]
	v_pk_add_f32 v[150:151], v[150:151], v[166:167]
	v_pk_add_f32 v[152:153], v[152:153], v[168:169]
	v_pk_add_f32 v[154:155], v[154:155], v[170:171]
	v_pk_add_f32 v[156:157], v[156:157], v[172:173]
	v_pk_add_f32 v[158:159], v[158:159], v[166:167]
	v_pk_add_f32 v[160:161], v[160:161], v[168:169]
	v_pk_add_f32 v[162:163], v[162:163], v[170:171]
	v_pk_add_f32 v[164:165], v[164:165], v[172:173]
	v_lshlrev_b32_e32 v166, 16, v58
	v_and_b32_e32 v167, 0xffff0000, v58
	v_lshlrev_b32_e32 v168, 16, v59
	v_and_b32_e32 v169, 0xffff0000, v59
	v_lshlrev_b32_e32 v170, 16, v60
	v_and_b32_e32 v171, 0xffff0000, v60
	v_lshlrev_b32_e32 v172, 16, v61
; #define GAS __attribute__((address_space(1)))
; __device__ __forceinline__ void prep_phase(Frame& F, CArgs a, int l, unsigned long long& tm_acc) {
;     ...
;             auto body = [&](auto WC) { constexpr int W = decltype(WC)::value;
;                 u32x4 v[W]; float mk[W];
; #pragma unroll
;                 for (int j = 0; j < W; ++j) { const int tt = t - W / 2 + j; const bool ok = tt >= 0 && tt < L; mk[j] = ok ? 1.f : 0.f; cnt += ok ? 1 : 0; v[j] = *(const GAS u32x4*)(zc + (size_t)(ok ? tt : t) * DIN); }
; #pragma unroll
;                 for (int j = 0; j < W; ++j) { s[0] += mk[j] * bflo(v[j].x); s[1] += mk[j] * bfhi(v[j].x); s[2] += mk[j] * bflo(v[j].y); s[3] += mk[j] * bfhi(v[j].y);
;                     s[4] += mk[j] * bflo(v[j].z); s[5] += mk[j] * bfhi(v[j].z); s[6] += mk[j] * bflo(v[j].w); s[7] += mk[j] * bfhi(v[j].w); } };
	v_and_b32_e32 v173, 0xffff0000, v61
	v_pk_add_f32 v[102:103], v[102:103], v[166:167]
	v_pk_add_f32 v[104:105], v[104:105], v[168:169]
	v_pk_add_f32 v[106:107], v[106:107], v[170:171]
	v_pk_add_f32 v[108:109], v[108:109], v[172:173]
	v_pk_add_f32 v[110:111], v[110:111], v[166:167]
	v_pk_add_f32 v[112:113], v[112:113], v[168:169]
	v_pk_add_f32 v[114:115], v[114:115], v[170:171]
	v_pk_add_f32 v[116:117], v[116:117], v[172:173]
	v_pk_add_f32 v[118:119], v[118:119], v[166:167]
	v_pk_add_f32 v[120:121], v[120:121], v[168:169]
	v_pk_add_f32 v[122:123], v[122:123], v[170:171]
	v_pk_add_f32 v[124:125], v[124:125], v[172:173]
	v_pk_add_f32 v[126:127], v[126:127], v[166:167]
	v_pk_add_f32 v[128:129], v[128:129], v[168:169]
	v_pk_add_f32 v[130:131], v[130:131], v[170:171]
	v_pk_add_f32 v[132:133], v[132:133], v[172:173]
	v_pk_add_f32 v[134:135], v[134:135], v[166:167]
	v_pk_add_f32 v[136:137], v[136:137], v[168:169]
	v_pk_add_f32 v[138:139], v[138:139], v[170:171]
	v_pk_add_f32 v[140:141], v[140:141], v[172:173]
	v_pk_add_f32 v[142:143], v[142:143], v[166:167]
	v_pk_add_f32 v[144:145], v[144:145], v[168:169]
	v_pk_add_f32 v[146:147], v[146:147], v[170:171]
	v_pk_add_f32 v[148:149], v[148:149], v[172:173]
	v_pk_add_f32 v[150:151], v[150:151], v[166:167]
	v_pk_add_f32 v[152:153], v[152:153], v[168:169]
	v_pk_add_f32 v[154:155], v[154:155], v[170:171]
	v_pk_add_f32 v[156:157], v[156:157], v[172:173]
	v_pk_add_f32 v[158:159], v[158:159], v[166:167]
	v_pk_add_f32 v[160:161], v[160:161], v[168:169]
	v_pk_add_f32 v[162:163], v[162:163], v[170:171]
	v_pk_add_f32 v[164:165], v[164:165], v[172:173]
	v_lshlrev_b32_e32 v166, 16, v62
	v_and_b32_e32 v167, 0xffff0000, v62
	v_lshlrev_b32_e32 v168, 16, v63
	v_and_b32_e32 v169, 0xffff0000, v63
	v_lshlrev_b32_e32 v170, 16, v64
	v_and_b32_e32 v171, 0xffff0000, v64
	v_lshlrev_b32_e32 v172, 16, v65
	v_and_b32_e32 v173, 0xffff0000, v65
	v_pk_add_f32 v[102:103], v[102:103], v[166:167]
	v_pk_add_f32 v[104:105], v[104:105], v[168:169]
	v_pk_add_f32 v[106:107], v[106:107], v[170:171]
	v_pk_add_f32 v[108:109], v[108:109], v[172:173]
	v_pk_add_f32 v[110:111], v[110:111], v[166:167]
	v_pk_add_f32 v[112:113], v[112:113], v[168:169]
	v_pk_add_f32 v[114:115], v[114:115], v[170:171]
	v_pk_add_f32 v[116:117], v[116:117], v[172:173]
	v_pk_add_f32 v[118:119], v[118:119], v[166:167]
	v_pk_add_f32 v[120:121], v[120:121], v[168:169]
	v_pk_add_f32 v[122:123], v[122:123], v[170:171]
	v_pk_add_f32 v[124:125], v[124:125], v[172:173]
	v_pk_add_f32 v[126:127], v[126:127], v[166:167]
	v_pk_add_f32 v[128:129], v[128:129], v[168:169]
	v_pk_add_f32 v[130:131], v[130:131], v[170:171]
	v_pk_add_f32 v[132:133], v[132:133], v[172:173]
	v_pk_add_f32 v[134:135], v[134:135], v[166:167]
	v_pk_add_f32 v[136:137], v[136:137], v[168:169]
	v_pk_add_f32 v[138:139], v[138:139], v[170:171]
	v_pk_add_f32 v[140:141], v[140:141], v[172:173]
	v_pk_add_f32 v[142:143], v[142:143], v[166:167]
	v_pk_add_f32 v[144:145], v[144:145], v[168:169]
	v_pk_add_f32 v[146:147], v[146:147], v[170:171]
	v_pk_add_f32 v[148:149], v[148:149], v[172:173]
	v_pk_add_f32 v[150:151], v[150:151], v[166:167]
	v_pk_add_f32 v[152:153], v[152:153], v[168:169]
	v_pk_add_f32 v[154:155], v[154:155], v[170:171]
	v_pk_add_f32 v[156:157], v[156:157], v[172:173]
	v_pk_add_f32 v[158:159], v[158:159], v[166:167]
	v_pk_add_f32 v[160:161], v[160:161], v[168:169]
	v_pk_add_f32 v[162:163], v[162:163], v[170:171]
	v_pk_add_f32 v[164:165], v[164:165], v[172:173]
	v_lshlrev_b32_e32 v166, 16, v66
	v_and_b32_e32 v167, 0xffff0000, v66
	v_lshlrev_b32_e32 v168, 16, v67
	v_and_b32_e32 v169, 0xffff0000, v67
	v_lshlrev_b32_e32 v170, 16, v68
	v_and_b32_e32 v171, 0xffff0000, v68
	v_lshlrev_b32_e32 v172, 16, v69
	v_and_b32_e32 v173, 0xffff0000, v69
	v_pk_add_f32 v[102:103], v[102:103], v[166:167]
	v_pk_add_f32 v[104:105], v[104:105], v[168:169]
	v_pk_add_f32 v[106:107], v[106:107], v[170:171]
	v_pk_add_f32 v[108:109], v[108:109], v[172:173]
	v_pk_add_f32 v[110:111], v[110:111], v[166:167]
	v_pk_add_f32 v[112:113], v[112:113], v[168:169]
	v_pk_add_f32 v[114:115], v[114:115], v[170:171]
	v_pk_add_f32 v[116:117], v[116:117], v[172:173]
	v_pk_add_f32 v[118:119], v[118:119], v[166:167]
	v_pk_add_f32 v[120:121], v[120:121], v[168:169]
	v_pk_add_f32 v[122:123], v[122:123], v[170:171]
	v_pk_add_f32 v[124:125], v[124:125], v[172:173]
	v_pk_add_f32 v[126:127], v[126:127], v[166:167]
	v_pk_add_f32 v[128:129], v[128:129], v[168:169]
	v_pk_add_f32 v[130:131], v[130:131], v[170:171]
	v_pk_add_f32 v[132:133], v[132:133], v[172:173]
	v_pk_add_f32 v[134:135], v[134:135], v[166:167]
	v_pk_add_f32 v[136:137], v[136:137], v[168:169]
	v_pk_add_f32 v[138:139], v[138:139], v[170:171]
	v_pk_add_f32 v[140:141], v[140:141], v[172:173]
	v_pk_add_f32 v[142:143], v[142:143], v[166:167]
	v_pk_add_f32 v[144:145], v[144:145], v[168:169]
	v_pk_add_f32 v[146:147], v[146:147], v[170:171]
	v_pk_add_f32 v[148:149], v[148:149], v[172:173]
	v_pk_add_f32 v[150:151], v[150:151], v[166:167]
	v_pk_add_f32 v[152:153], v[152:153], v[168:169]
	v_pk_add_f32 v[154:155], v[154:155], v[170:171]
	v_pk_add_f32 v[156:157], v[156:157], v[172:173]
	v_pk_add_f32 v[158:159], v[158:159], v[166:167]
	v_pk_add_f32 v[160:161], v[160:161], v[168:169]
	v_pk_add_f32 v[162:163], v[162:163], v[170:171]
	v_pk_add_f32 v[164:165], v[164:165], v[172:173]
	v_lshlrev_b32_e32 v166, 16, v70
	v_and_b32_e32 v167, 0xffff0000, v70
	v_lshlrev_b32_e32 v168, 16, v71
	v_and_b32_e32 v169, 0xffff0000, v71
	v_lshlrev_b32_e32 v170, 16, v72
	v_and_b32_e32 v171, 0xffff0000, v72
	v_lshlrev_b32_e32 v172, 16, v73
	v_and_b32_e32 v173, 0xffff0000, v73
	v_pk_add_f32 v[102:103], v[102:103], v[166:167]
; #define GAS __attribute__((address_space(1)))
; __device__ __forceinline__ void prep_phase(Frame& F, CArgs a, int l, unsigned long long& tm_acc) {
;     ...
;             auto body = [&](auto WC) { constexpr int W = decltype(WC)::value;
;                 u32x4 v[W]; float mk[W];
; #pragma unroll
;                 for (int j = 0; j < W; ++j) { const int tt = t - W / 2 + j; const bool ok = tt >= 0 && tt < L; mk[j] = ok ? 1.f : 0.f; cnt += ok ? 1 : 0; v[j] = *(const GAS u32x4*)(zc + (size_t)(ok ? tt : t) * DIN); }
; #pragma unroll
;                 for (int j = 0; j < W; ++j) { s[0] += mk[j] * bflo(v[j].x); s[1] += mk[j] * bfhi(v[j].x); s[2] += mk[j] * bflo(v[j].y); s[3] += mk[j] * bfhi(v[j].y);
;                     s[4] += mk[j] * bflo(v[j].z); s[5] += mk[j] * bfhi(v[j].z); s[6] += mk[j] * bflo(v[j].w); s[7] += mk[j] * bfhi(v[j].w); } };
	v_pk_add_f32 v[104:105], v[104:105], v[168:169]
	v_pk_add_f32 v[106:107], v[106:107], v[170:171]
	v_pk_add_f32 v[108:109], v[108:109], v[172:173]
	v_pk_add_f32 v[110:111], v[110:111], v[166:167]
	v_pk_add_f32 v[112:113], v[112:113], v[168:169]
	v_pk_add_f32 v[114:115], v[114:115], v[170:171]
	v_pk_add_f32 v[116:117], v[116:117], v[172:173]
	v_pk_add_f32 v[118:119], v[118:119], v[166:167]
	v_pk_add_f32 v[120:121], v[120:121], v[168:169]
	v_pk_add_f32 v[122:123], v[122:123], v[170:171]
	v_pk_add_f32 v[124:125], v[124:125], v[172:173]
	v_pk_add_f32 v[126:127], v[126:127], v[166:167]
	v_pk_add_f32 v[128:129], v[128:129], v[168:169]
	v_pk_add_f32 v[130:131], v[130:131], v[170:171]
	v_pk_add_f32 v[132:133], v[132:133], v[172:173]
	v_pk_add_f32 v[134:135], v[134:135], v[166:167]
	v_pk_add_f32 v[136:137], v[136:137], v[168:169]
	v_pk_add_f32 v[138:139], v[138:139], v[170:171]
	v_pk_add_f32 v[140:141], v[140:141], v[172:173]
	v_pk_add_f32 v[142:143], v[142:143], v[166:167]
	v_pk_add_f32 v[144:145], v[144:145], v[168:169]
	v_pk_add_f32 v[146:147], v[146:147], v[170:171]
	v_pk_add_f32 v[148:149], v[148:149], v[172:173]
	v_pk_add_f32 v[150:151], v[150:151], v[166:167]
	v_pk_add_f32 v[152:153], v[152:153], v[168:169]
	v_pk_add_f32 v[154:155], v[154:155], v[170:171]
	v_pk_add_f32 v[156:157], v[156:157], v[172:173]
	v_pk_add_f32 v[158:159], v[158:159], v[166:167]
	v_pk_add_f32 v[160:161], v[160:161], v[168:169]
	v_pk_add_f32 v[162:163], v[162:163], v[170:171]
	v_pk_add_f32 v[164:165], v[164:165], v[172:173]
	v_lshlrev_b32_e32 v166, 16, v74
	v_and_b32_e32 v167, 0xffff0000, v74
	v_lshlrev_b32_e32 v168, 16, v75
	v_and_b32_e32 v169, 0xffff0000, v75
	v_lshlrev_b32_e32 v170, 16, v76
	v_and_b32_e32 v171, 0xffff0000, v76
	v_lshlrev_b32_e32 v172, 16, v77
	v_and_b32_e32 v173, 0xffff0000, v77
	v_pk_add_f32 v[110:111], v[110:111], v[166:167]
	v_pk_add_f32 v[112:113], v[112:113], v[168:169]
	v_pk_add_f32 v[114:115], v[114:115], v[170:171]
	v_pk_add_f32 v[116:117], v[116:117], v[172:173]
	v_pk_add_f32 v[118:119], v[118:119], v[166:167]
	v_pk_add_f32 v[120:121], v[120:121], v[168:169]
	v_pk_add_f32 v[122:123], v[122:123], v[170:171]
	v_pk_add_f32 v[124:125], v[124:125], v[172:173]
	v_pk_add_f32 v[126:127], v[126:127], v[166:167]
	v_pk_add_f32 v[128:129], v[128:129], v[168:169]
	v_pk_add_f32 v[130:131], v[130:131], v[170:171]
	v_pk_add_f32 v[132:133], v[132:133], v[172:173]
	v_pk_add_f32 v[134:135], v[134:135], v[166:167]
	v_pk_add_f32 v[136:137], v[136:137], v[168:169]
	v_pk_add_f32 v[138:139], v[138:139], v[170:171]
	v_pk_add_f32 v[140:141], v[140:141], v[172:173]
	v_pk_add_f32 v[142:143], v[142:143], v[166:167]
	v_pk_add_f32 v[144:145], v[144:145], v[168:169]
	v_pk_add_f32 v[146:147], v[146:147], v[170:171]
	v_pk_add_f32 v[148:149], v[148:149], v[172:173]
	v_pk_add_f32 v[150:151], v[150:151], v[166:167]
	v_pk_add_f32 v[152:153], v[152:153], v[168:169]
	v_pk_add_f32 v[154:155], v[154:155], v[170:171]
	v_pk_add_f32 v[156:157], v[156:157], v[172:173]
	v_pk_add_f32 v[158:159], v[158:159], v[166:167]
	v_pk_add_f32 v[160:161], v[160:161], v[168:169]
	v_pk_add_f32 v[162:163], v[162:163], v[170:171]
	v_pk_add_f32 v[164:165], v[164:165], v[172:173]
	v_lshlrev_b32_e32 v166, 16, v78
	v_and_b32_e32 v167, 0xffff0000, v78
	v_lshlrev_b32_e32 v168, 16, v79
	v_and_b32_e32 v169, 0xffff0000, v79
	v_lshlrev_b32_e32 v170, 16, v80
	v_and_b32_e32 v171, 0xffff0000, v80
	v_lshlrev_b32_e32 v172, 16, v81
	v_and_b32_e32 v173, 0xffff0000, v81
	v_pk_add_f32 v[118:119], v[118:119], v[166:167]
	v_pk_add_f32 v[120:121], v[120:121], v[168:169]
	v_pk_add_f32 v[122:123], v[122:123], v[170:171]
	v_pk_add_f32 v[124:125], v[124:125], v[172:173]
	v_pk_add_f32 v[126:127], v[126:127], v[166:167]
	v_pk_add_f32 v[128:129], v[128:129], v[168:169]
	v_pk_add_f32 v[130:131], v[130:131], v[170:171]
	v_pk_add_f32 v[132:133], v[132:133], v[172:173]
	v_pk_add_f32 v[134:135], v[134:135], v[166:167]
	v_pk_add_f32 v[136:137], v[136:137], v[168:169]
	v_pk_add_f32 v[138:139], v[138:139], v[170:171]
	v_pk_add_f32 v[140:141], v[140:141], v[172:173]
	v_pk_add_f32 v[142:143], v[142:143], v[166:167]
	v_pk_add_f32 v[144:145], v[144:145], v[168:169]
	v_pk_add_f32 v[146:147], v[146:147], v[170:171]
	v_pk_add_f32 v[148:149], v[148:149], v[172:173]
	v_pk_add_f32 v[150:151], v[150:151], v[166:167]
	v_pk_add_f32 v[152:153], v[152:153], v[168:169]
	v_pk_add_f32 v[154:155], v[154:155], v[170:171]
	v_pk_add_f32 v[156:157], v[156:157], v[172:173]
	v_pk_add_f32 v[158:159], v[158:159], v[166:167]
	v_pk_add_f32 v[160:161], v[160:161], v[168:169]
	v_pk_add_f32 v[162:163], v[162:163], v[170:171]
	v_pk_add_f32 v[164:165], v[164:165], v[172:173]
	v_lshlrev_b32_e32 v166, 16, v82
	v_and_b32_e32 v167, 0xffff0000, v82
	v_lshlrev_b32_e32 v168, 16, v83
	v_and_b32_e32 v169, 0xffff0000, v83
	v_lshlrev_b32_e32 v170, 16, v84
	v_and_b32_e32 v171, 0xffff0000, v84
	v_lshlrev_b32_e32 v172, 16, v85
	v_and_b32_e32 v173, 0xffff0000, v85
	v_pk_add_f32 v[126:127], v[126:127], v[166:167]
	v_pk_add_f32 v[128:129], v[128:129], v[168:169]
	v_pk_add_f32 v[130:131], v[130:131], v[170:171]
	v_pk_add_f32 v[132:133], v[132:133], v[172:173]
	v_pk_add_f32 v[134:135], v[134:135], v[166:167]
	v_pk_add_f32 v[136:137], v[136:137], v[168:169]
	v_pk_add_f32 v[138:139], v[138:139], v[170:171]
	v_pk_add_f32 v[140:141], v[140:141], v[172:173]
	v_pk_add_f32 v[142:143], v[142:143], v[166:167]
	v_pk_add_f32 v[144:145], v[144:145], v[168:169]
	v_pk_add_f32 v[146:147], v[146:147], v[170:171]
	v_pk_add_f32 v[148:149], v[148:149], v[172:173]
	v_pk_add_f32 v[150:151], v[150:151], v[166:167]
	v_pk_add_f32 v[152:153], v[152:153], v[168:169]
	v_pk_add_f32 v[154:155], v[154:155], v[170:171]
; #define GAS __attribute__((address_space(1)))
; __device__ __forceinline__ void prep_phase(Frame& F, CArgs a, int l, unsigned long long& tm_acc) {
;     ...
;             auto body = [&](auto WC) { constexpr int W = decltype(WC)::value;
;                 u32x4 v[W]; float mk[W];
; #pragma unroll
;                 for (int j = 0; j < W; ++j) { const int tt = t - W / 2 + j; const bool ok = tt >= 0 && tt < L; mk[j] = ok ? 1.f : 0.f; cnt += ok ? 1 : 0; v[j] = *(const GAS u32x4*)(zc + (size_t)(ok ? tt : t) * DIN); }
; #pragma unroll
;                 for (int j = 0; j < W; ++j) { s[0] += mk[j] * bflo(v[j].x); s[1] += mk[j] * bfhi(v[j].x); s[2] += mk[j] * bflo(v[j].y); s[3] += mk[j] * bfhi(v[j].y);
;                     s[4] += mk[j] * bflo(v[j].z); s[5] += mk[j] * bfhi(v[j].z); s[6] += mk[j] * bflo(v[j].w); s[7] += mk[j] * bfhi(v[j].w); } };
	v_pk_add_f32 v[156:157], v[156:157], v[172:173]
	v_pk_add_f32 v[158:159], v[158:159], v[166:167]
	v_pk_add_f32 v[160:161], v[160:161], v[168:169]
	v_pk_add_f32 v[162:163], v[162:163], v[170:171]
	v_pk_add_f32 v[164:165], v[164:165], v[172:173]
	v_lshlrev_b32_e32 v166, 16, v86
	v_and_b32_e32 v167, 0xffff0000, v86
	v_lshlrev_b32_e32 v168, 16, v87
	v_and_b32_e32 v169, 0xffff0000, v87
	v_lshlrev_b32_e32 v170, 16, v88
	v_and_b32_e32 v171, 0xffff0000, v88
	v_lshlrev_b32_e32 v172, 16, v89
	v_and_b32_e32 v173, 0xffff0000, v89
	v_pk_add_f32 v[134:135], v[134:135], v[166:167]
	v_pk_add_f32 v[136:137], v[136:137], v[168:169]
	v_pk_add_f32 v[138:139], v[138:139], v[170:171]
	v_pk_add_f32 v[140:141], v[140:141], v[172:173]
	v_pk_add_f32 v[142:143], v[142:143], v[166:167]
	v_pk_add_f32 v[144:145], v[144:145], v[168:169]
	v_pk_add_f32 v[146:147], v[146:147], v[170:171]
	v_pk_add_f32 v[148:149], v[148:149], v[172:173]
	v_pk_add_f32 v[150:151], v[150:151], v[166:167]
	v_pk_add_f32 v[152:153], v[152:153], v[168:169]
	v_pk_add_f32 v[154:155], v[154:155], v[170:171]
	v_pk_add_f32 v[156:157], v[156:157], v[172:173]
	v_pk_add_f32 v[158:159], v[158:159], v[166:167]
	v_pk_add_f32 v[160:161], v[160:161], v[168:169]
	v_pk_add_f32 v[162:163], v[162:163], v[170:171]
	v_pk_add_f32 v[164:165], v[164:165], v[172:173]
	v_lshlrev_b32_e32 v166, 16, v90
	v_and_b32_e32 v167, 0xffff0000, v90
	v_lshlrev_b32_e32 v168, 16, v91
	v_and_b32_e32 v169, 0xffff0000, v91
	v_lshlrev_b32_e32 v170, 16, v92
	v_and_b32_e32 v171, 0xffff0000, v92
	v_lshlrev_b32_e32 v172, 16, v93
	v_and_b32_e32 v173, 0xffff0000, v93
	v_pk_add_f32 v[142:143], v[142:143], v[166:167]
	v_pk_add_f32 v[144:145], v[144:145], v[168:169]
	v_pk_add_f32 v[146:147], v[146:147], v[170:171]
	v_pk_add_f32 v[148:149], v[148:149], v[172:173]
	v_pk_add_f32 v[150:151], v[150:151], v[166:167]
	v_pk_add_f32 v[152:153], v[152:153], v[168:169]
	v_pk_add_f32 v[154:155], v[154:155], v[170:171]
	v_pk_add_f32 v[156:157], v[156:157], v[172:173]
	v_pk_add_f32 v[158:159], v[158:159], v[166:167]
	v_pk_add_f32 v[160:161], v[160:161], v[168:169]
	v_pk_add_f32 v[162:163], v[162:163], v[170:171]
	v_pk_add_f32 v[164:165], v[164:165], v[172:173]
	v_lshlrev_b32_e32 v166, 16, v94
	v_and_b32_e32 v167, 0xffff0000, v94
	v_lshlrev_b32_e32 v168, 16, v95
	v_and_b32_e32 v169, 0xffff0000, v95
	v_lshlrev_b32_e32 v170, 16, v96
	v_and_b32_e32 v171, 0xffff0000, v96
	v_lshlrev_b32_e32 v172, 16, v97
	v_and_b32_e32 v173, 0xffff0000, v97
	v_pk_add_f32 v[150:151], v[150:151], v[166:167]
	v_pk_add_f32 v[152:153], v[152:153], v[168:169]
	v_pk_add_f32 v[154:155], v[154:155], v[170:171]
	v_pk_add_f32 v[156:157], v[156:157], v[172:173]
	v_pk_add_f32 v[158:159], v[158:159], v[166:167]
	v_pk_add_f32 v[160:161], v[160:161], v[168:169]
	v_pk_add_f32 v[162:163], v[162:163], v[170:171]
	v_pk_add_f32 v[164:165], v[164:165], v[172:173]
	v_lshlrev_b32_e32 v166, 16, v98
	v_and_b32_e32 v167, 0xffff0000, v98
	v_lshlrev_b32_e32 v168, 16, v99
	v_and_b32_e32 v169, 0xffff0000, v99
	v_lshlrev_b32_e32 v170, 16, v100
	v_and_b32_e32 v171, 0xffff0000, v100
	v_lshlrev_b32_e32 v172, 16, v101
	v_and_b32_e32 v173, 0xffff0000, v101
	v_pk_add_f32 v[158:159], v[158:159], v[166:167]
	v_pk_add_f32 v[160:161], v[160:161], v[168:169]
	v_pk_add_f32 v[162:163], v[162:163], v[170:171]
	v_pk_add_f32 v[164:165], v[164:165], v[172:173]
	s_branch .Lhp_fin
.Lhp_w2:
	v_add_u32_e32 v3, -4, v4
	v_mul_lo_u32 v2, v3, s22
	v_add_u32_e32 v2, v2, v5
	v_cmp_gt_u32_e64 s[18:19], s9, v3
	s_nop 1
	s_mov_b64 exec, s[18:19]
	global_load_dwordx4 v[26:29], v2, s[14:15]
	s_mov_b64 exec, -1
	v_add_u32_e32 v3, 1, v3
	v_add_u32_e32 v2, s22, v2
	v_cmp_gt_u32_e64 s[18:19], s9, v3
	s_nop 1
	s_mov_b64 exec, s[18:19]
	global_load_dwordx4 v[30:33], v2, s[14:15]
	s_mov_b64 exec, -1
	v_add_u32_e32 v3, 1, v3
	v_add_u32_e32 v2, s22, v2
	v_cmp_gt_u32_e64 s[18:19], s9, v3
	s_nop 1
	s_mov_b64 exec, s[18:19]
	global_load_dwordx4 v[34:37], v2, s[14:15]
	s_mov_b64 exec, -1
	v_add_u32_e32 v3, 1, v3
	v_add_u32_e32 v2, s22, v2
	v_cmp_gt_u32_e64 s[18:19], s9, v3
	s_nop 1
	s_mov_b64 exec, s[18:19]
	global_load_dwordx4 v[38:41], v2, s[14:15]
	s_mov_b64 exec, -1
	v_add_u32_e32 v3, 1, v3
	v_add_u32_e32 v2, s22, v2
	v_cmp_gt_u32_e64 s[18:19], s9, v3
	s_nop 1
	s_mov_b64 exec, s[18:19]
	global_load_dwordx4 v[42:45], v2, s[14:15]
	s_mov_b64 exec, -1
	v_add_u32_e32 v3, 1, v3
	v_add_u32_e32 v2, s22, v2
	v_cmp_gt_u32_e64 s[18:19], s9, v3
	s_nop 1
	s_mov_b64 exec, s[18:19]
	global_load_dwordx4 v[46:49], v2, s[14:15]
	s_mov_b64 exec, -1
	v_add_u32_e32 v3, 1, v3
	v_add_u32_e32 v2, s22, v2
	v_cmp_gt_u32_e64 s[18:19], s9, v3
	s_nop 1
	s_mov_b64 exec, s[18:19]
	global_load_dwordx4 v[50:53], v2, s[14:15]
	s_mov_b64 exec, -1
	v_add_u32_e32 v3, 1, v3
	v_add_u32_e32 v2, s22, v2
	v_cmp_gt_u32_e64 s[18:19], s9, v3
	s_nop 1
	s_mov_b64 exec, s[18:19]
	global_load_dwordx4 v[54:57], v2, s[14:15]
	s_mov_b64 exec, -1
	v_add_u32_e32 v3, 1, v3
	v_add_u32_e32 v2, s22, v2
	v_cmp_gt_u32_e64 s[18:19], s9, v3
	s_nop 1
	s_mov_b64 exec, s[18:19]
	global_load_dwordx4 v[58:61], v2, s[14:15]
	s_mov_b64 exec, -1
	v_add_u32_e32 v3, 1, v3
	v_add_u32_e32 v2, s22, v2
	v_cmp_gt_u32_e64 s[18:19], s9, v3
	s_nop 1
	s_mov_b64 exec, s[18:19]
	global_load_dwordx4 v[62:65], v2, s[14:15]
	s_mov_b64 exec, -1
	v_add_u32_e32 v3, 1, v3
	v_add_u32_e32 v2, s22, v2
	v_cmp_gt_u32_e64 s[18:19], s9, v3
	s_nop 1
	s_mov_b64 exec, s[18:19]
	global_load_dwordx4 v[66:69], v2, s[14:15]
	s_mov_b64 exec, -1
	v_add_u32_e32 v3, 1, v3
	v_add_u32_e32 v2, s22, v2
	v_cmp_gt_u32_e64 s[18:19], s9, v3
	s_nop 1
	s_mov_b64 exec, s[18:19]
	global_load_dwordx4 v[70:73], v2, s[14:15]
	s_mov_b64 exec, -1
	v_add_u32_e32 v3, 1, v3
	v_add_u32_e32 v2, s22, v2
	v_cmp_gt_u32_e64 s[18:19], s9, v3
	s_nop 1
	s_mov_b64 exec, s[18:19]
	global_load_dwordx4 v[74:77], v2, s[14:15]
	s_mov_b64 exec, -1
	v_add_u32_e32 v3, 1, v3
	v_add_u32_e32 v2, s22, v2
	v_cmp_gt_u32_e64 s[18:19], s9, v3
	s_nop 1
	s_mov_b64 exec, s[18:19]
	global_load_dwordx4 v[78:81], v2, s[14:15]
	s_mov_b64 exec, -1
	v_add_u32_e32 v3, 1, v3
	v_add_u32_e32 v2, s22, v2
	v_cmp_gt_u32_e64 s[18:19], s9, v3
	s_nop 1
	s_mov_b64 exec, s[18:19]
	global_load_dwordx4 v[82:85], v2, s[14:15]
	s_mov_b64 exec, -1
	s_waitcnt vmcnt(0)
; #define GAS __attribute__((address_space(1)))
; __device__ __forceinline__ void prep_phase(Frame& F, CArgs a, int l, unsigned long long& tm_acc) {
;     ...
;             auto body = [&](auto WC) { constexpr int W = decltype(WC)::value;
;                 u32x4 v[W]; float mk[W];
; #pragma unroll
;                 for (int j = 0; j < W; ++j) { const int tt = t - W / 2 + j; const bool ok = tt >= 0 && tt < L; mk[j] = ok ? 1.f : 0.f; cnt += ok ? 1 : 0; v[j] = *(const GAS u32x4*)(zc + (size_t)(ok ? tt : t) * DIN); }
; #pragma unroll
;                 for (int j = 0; j < W; ++j) { s[0] += mk[j] * bflo(v[j].x); s[1] += mk[j] * bfhi(v[j].x); s[2] += mk[j] * bflo(v[j].y); s[3] += mk[j] * bfhi(v[j].y);
;                     s[4] += mk[j] * bflo(v[j].z); s[5] += mk[j] * bfhi(v[j].z); s[6] += mk[j] * bflo(v[j].w); s[7] += mk[j] * bfhi(v[j].w); } };
	v_lshlrev_b32_e32 v166, 16, v26
	v_and_b32_e32 v167, 0xffff0000, v26
	v_lshlrev_b32_e32 v168, 16, v27
	v_and_b32_e32 v169, 0xffff0000, v27
	v_lshlrev_b32_e32 v170, 16, v28
	v_and_b32_e32 v171, 0xffff0000, v28
	v_lshlrev_b32_e32 v172, 16, v29
	v_and_b32_e32 v173, 0xffff0000, v29
	v_pk_add_f32 v[102:103], v[102:103], v[166:167]
	v_pk_add_f32 v[104:105], v[104:105], v[168:169]
	v_pk_add_f32 v[106:107], v[106:107], v[170:171]
	v_pk_add_f32 v[108:109], v[108:109], v[172:173]
	v_lshlrev_b32_e32 v166, 16, v30
	v_and_b32_e32 v167, 0xffff0000, v30
	v_lshlrev_b32_e32 v168, 16, v31
	v_and_b32_e32 v169, 0xffff0000, v31
	v_lshlrev_b32_e32 v170, 16, v32
	v_and_b32_e32 v171, 0xffff0000, v32
	v_lshlrev_b32_e32 v172, 16, v33
	v_and_b32_e32 v173, 0xffff0000, v33
	v_pk_add_f32 v[102:103], v[102:103], v[166:167]
	v_pk_add_f32 v[104:105], v[104:105], v[168:169]
	v_pk_add_f32 v[106:107], v[106:107], v[170:171]
	v_pk_add_f32 v[108:109], v[108:109], v[172:173]
	v_pk_add_f32 v[110:111], v[110:111], v[166:167]
	v_pk_add_f32 v[112:113], v[112:113], v[168:169]
	v_pk_add_f32 v[114:115], v[114:115], v[170:171]
	v_pk_add_f32 v[116:117], v[116:117], v[172:173]
	v_lshlrev_b32_e32 v166, 16, v34
	v_and_b32_e32 v167, 0xffff0000, v34
	v_lshlrev_b32_e32 v168, 16, v35
	v_and_b32_e32 v169, 0xffff0000, v35
	v_lshlrev_b32_e32 v170, 16, v36
	v_and_b32_e32 v171, 0xffff0000, v36
	v_lshlrev_b32_e32 v172, 16, v37
	v_and_b32_e32 v173, 0xffff0000, v37
	v_pk_add_f32 v[102:103], v[102:103], v[166:167]
	v_pk_add_f32 v[104:105], v[104:105], v[168:169]
	v_pk_add_f32 v[106:107], v[106:107], v[170:171]
	v_pk_add_f32 v[108:109], v[108:109], v[172:173]
	v_pk_add_f32 v[110:111], v[110:111], v[166:167]
	v_pk_add_f32 v[112:113], v[112:113], v[168:169]
	v_pk_add_f32 v[114:115], v[114:115], v[170:171]
	v_pk_add_f32 v[116:117], v[116:117], v[172:173]
	v_pk_add_f32 v[118:119], v[118:119], v[166:167]
	v_pk_add_f32 v[120:121], v[120:121], v[168:169]
	v_pk_add_f32 v[122:123], v[122:123], v[170:171]
	v_pk_add_f32 v[124:125], v[124:125], v[172:173]
	v_lshlrev_b32_e32 v166, 16, v38
	v_and_b32_e32 v167, 0xffff0000, v38
	v_lshlrev_b32_e32 v168, 16, v39
	v_and_b32_e32 v169, 0xffff0000, v39
	v_lshlrev_b32_e32 v170, 16, v40
	v_and_b32_e32 v171, 0xffff0000, v40
	v_lshlrev_b32_e32 v172, 16, v41
	v_and_b32_e32 v173, 0xffff0000, v41
	v_pk_add_f32 v[102:103], v[102:103], v[166:167]
	v_pk_add_f32 v[104:105], v[104:105], v[168:169]
	v_pk_add_f32 v[106:107], v[106:107], v[170:171]
	v_pk_add_f32 v[108:109], v[108:109], v[172:173]
	v_pk_add_f32 v[110:111], v[110:111], v[166:167]
	v_pk_add_f32 v[112:113], v[112:113], v[168:169]
	v_pk_add_f32 v[114:115], v[114:115], v[170:171]
	v_pk_add_f32 v[116:117], v[116:117], v[172:173]
	v_pk_add_f32 v[118:119], v[118:119], v[166:167]
	v_pk_add_f32 v[120:121], v[120:121], v[168:169]
	v_pk_add_f32 v[122:123], v[122:123], v[170:171]
	v_pk_add_f32 v[124:125], v[124:125], v[172:173]
	v_pk_add_f32 v[126:127], v[126:127], v[166:167]
	v_pk_add_f32 v[128:129], v[128:129], v[168:169]
	v_pk_add_f32 v[130:131], v[130:131], v[170:171]
	v_pk_add_f32 v[132:133], v[132:133], v[172:173]
	v_lshlrev_b32_e32 v166, 16, v42
	v_and_b32_e32 v167, 0xffff0000, v42
	v_lshlrev_b32_e32 v168, 16, v43
	v_and_b32_e32 v169, 0xffff0000, v43
	v_lshlrev_b32_e32 v170, 16, v44
	v_and_b32_e32 v171, 0xffff0000, v44
	v_lshlrev_b32_e32 v172, 16, v45
	v_and_b32_e32 v173, 0xffff0000, v45
	v_pk_add_f32 v[102:103], v[102:103], v[166:167]
	v_pk_add_f32 v[104:105], v[104:105], v[168:169]
	v_pk_add_f32 v[106:107], v[106:107], v[170:171]
	v_pk_add_f32 v[108:109], v[108:109], v[172:173]
	v_pk_add_f32 v[110:111], v[110:111], v[166:167]
	v_pk_add_f32 v[112:113], v[112:113], v[168:169]
	v_pk_add_f32 v[114:115], v[114:115], v[170:171]
	v_pk_add_f32 v[116:117], v[116:117], v[172:173]
	v_pk_add_f32 v[118:119], v[118:119], v[166:167]
	v_pk_add_f32 v[120:121], v[120:121], v[168:169]
	v_pk_add_f32 v[122:123], v[122:123], v[170:171]
	v_pk_add_f32 v[124:125], v[124:125], v[172:173]
	v_pk_add_f32 v[126:127], v[126:127], v[166:167]
	v_pk_add_f32 v[128:129], v[128:129], v[168:169]
	v_pk_add_f32 v[130:131], v[130:131], v[170:171]
	v_pk_add_f32 v[132:133], v[132:133], v[172:173]
	v_pk_add_f32 v[134:135], v[134:135], v[166:167]
	v_pk_add_f32 v[136:137], v[136:137], v[168:169]
	v_pk_add_f32 v[138:139], v[138:139], v[170:171]
	v_pk_add_f32 v[140:141], v[140:141], v[172:173]
	v_lshlrev_b32_e32 v166, 16, v46
	v_and_b32_e32 v167, 0xffff0000, v46
	v_lshlrev_b32_e32 v168, 16, v47
	v_and_b32_e32 v169, 0xffff0000, v47
	v_lshlrev_b32_e32 v170, 16, v48
	v_and_b32_e32 v171, 0xffff0000, v48
	v_lshlrev_b32_e32 v172, 16, v49
	v_and_b32_e32 v173, 0xffff0000, v49
	v_pk_add_f32 v[102:103], v[102:103], v[166:167]
	v_pk_add_f32 v[104:105], v[104:105], v[168:169]
	v_pk_add_f32 v[106:107], v[106:107], v[170:171]
	v_pk_add_f32 v[108:109], v[108:109], v[172:173]
	v_pk_add_f32 v[110:111], v[110:111], v[166:167]
	v_pk_add_f32 v[112:113], v[112:113], v[168:169]
	v_pk_add_f32 v[114:115], v[114:115], v[170:171]
	v_pk_add_f32 v[116:117], v[116:117], v[172:173]
	v_pk_add_f32 v[118:119], v[118:119], v[166:167]
	v_pk_add_f32 v[120:121], v[120:121], v[168:169]
	v_pk_add_f32 v[122:123], v[122:123], v[170:171]
	v_pk_add_f32 v[124:125], v[124:125], v[172:173]
	v_pk_add_f32 v[126:127], v[126:127], v[166:167]
	v_pk_add_f32 v[128:129], v[128:129], v[168:169]
	v_pk_add_f32 v[130:131], v[130:131], v[170:171]
	v_pk_add_f32 v[132:133], v[132:133], v[172:173]
	v_pk_add_f32 v[134:135], v[134:135], v[166:167]
	v_pk_add_f32 v[136:137], v[136:137], v[168:169]
	v_pk_add_f32 v[138:139], v[138:139], v[170:171]
	v_pk_add_f32 v[140:141], v[140:141], v[172:173]
	v_pk_add_f32 v[142:143], v[142:143], v[166:167]
; #define GAS __attribute__((address_space(1)))
; __device__ __forceinline__ void prep_phase(Frame& F, CArgs a, int l, unsigned long long& tm_acc) {
;     ...
;             auto body = [&](auto WC) { constexpr int W = decltype(WC)::value;
;                 u32x4 v[W]; float mk[W];
; #pragma unroll
;                 for (int j = 0; j < W; ++j) { const int tt = t - W / 2 + j; const bool ok = tt >= 0 && tt < L; mk[j] = ok ? 1.f : 0.f; cnt += ok ? 1 : 0; v[j] = *(const GAS u32x4*)(zc + (size_t)(ok ? tt : t) * DIN); }
; #pragma unroll
;                 for (int j = 0; j < W; ++j) { s[0] += mk[j] * bflo(v[j].x); s[1] += mk[j] * bfhi(v[j].x); s[2] += mk[j] * bflo(v[j].y); s[3] += mk[j] * bfhi(v[j].y);
;                     s[4] += mk[j] * bflo(v[j].z); s[5] += mk[j] * bfhi(v[j].z); s[6] += mk[j] * bflo(v[j].w); s[7] += mk[j] * bfhi(v[j].w); } };
	v_pk_add_f32 v[144:145], v[144:145], v[168:169]
	v_pk_add_f32 v[146:147], v[146:147], v[170:171]
	v_pk_add_f32 v[148:149], v[148:149], v[172:173]
	v_lshlrev_b32_e32 v166, 16, v50
	v_and_b32_e32 v167, 0xffff0000, v50
	v_lshlrev_b32_e32 v168, 16, v51
	v_and_b32_e32 v169, 0xffff0000, v51
	v_lshlrev_b32_e32 v170, 16, v52
	v_and_b32_e32 v171, 0xffff0000, v52
	v_lshlrev_b32_e32 v172, 16, v53
	v_and_b32_e32 v173, 0xffff0000, v53
	v_pk_add_f32 v[102:103], v[102:103], v[166:167]
	v_pk_add_f32 v[104:105], v[104:105], v[168:169]
	v_pk_add_f32 v[106:107], v[106:107], v[170:171]
	v_pk_add_f32 v[108:109], v[108:109], v[172:173]
	v_pk_add_f32 v[110:111], v[110:111], v[166:167]
	v_pk_add_f32 v[112:113], v[112:113], v[168:169]
	v_pk_add_f32 v[114:115], v[114:115], v[170:171]
	v_pk_add_f32 v[116:117], v[116:117], v[172:173]
	v_pk_add_f32 v[118:119], v[118:119], v[166:167]
	v_pk_add_f32 v[120:121], v[120:121], v[168:169]
	v_pk_add_f32 v[122:123], v[122:123], v[170:171]
	v_pk_add_f32 v[124:125], v[124:125], v[172:173]
	v_pk_add_f32 v[126:127], v[126:127], v[166:167]
	v_pk_add_f32 v[128:129], v[128:129], v[168:169]
	v_pk_add_f32 v[130:131], v[130:131], v[170:171]
	v_pk_add_f32 v[132:133], v[132:133], v[172:173]
	v_pk_add_f32 v[134:135], v[134:135], v[166:167]
	v_pk_add_f32 v[136:137], v[136:137], v[168:169]
	v_pk_add_f32 v[138:139], v[138:139], v[170:171]
	v_pk_add_f32 v[140:141], v[140:141], v[172:173]
	v_pk_add_f32 v[142:143], v[142:143], v[166:167]
	v_pk_add_f32 v[144:145], v[144:145], v[168:169]
	v_pk_add_f32 v[146:147], v[146:147], v[170:171]
	v_pk_add_f32 v[148:149], v[148:149], v[172:173]
	v_pk_add_f32 v[150:151], v[150:151], v[166:167]
	v_pk_add_f32 v[152:153], v[152:153], v[168:169]
	v_pk_add_f32 v[154:155], v[154:155], v[170:171]
	v_pk_add_f32 v[156:157], v[156:157], v[172:173]
	v_lshlrev_b32_e32 v166, 16, v54
	v_and_b32_e32 v167, 0xffff0000, v54
	v_lshlrev_b32_e32 v168, 16, v55
	v_and_b32_e32 v169, 0xffff0000, v55
	v_lshlrev_b32_e32 v170, 16, v56
	v_and_b32_e32 v171, 0xffff0000, v56
	v_lshlrev_b32_e32 v172, 16, v57
	v_and_b32_e32 v173, 0xffff0000, v57
	v_pk_add_f32 v[102:103], v[102:103], v[166:167]
	v_pk_add_f32 v[104:105], v[104:105], v[168:169]
	v_pk_add_f32 v[106:107], v[106:107], v[170:171]
	v_pk_add_f32 v[108:109], v[108:109], v[172:173]
	v_pk_add_f32 v[110:111], v[110:111], v[166:167]
	v_pk_add_f32 v[112:113], v[112:113], v[168:169]
	v_pk_add_f32 v[114:115], v[114:115], v[170:171]
	v_pk_add_f32 v[116:117], v[116:117], v[172:173]
	v_pk_add_f32 v[118:119], v[118:119], v[166:167]
	v_pk_add_f32 v[120:121], v[120:121], v[168:169]
	v_pk_add_f32 v[122:123], v[122:123], v[170:171]
	v_pk_add_f32 v[124:125], v[124:125], v[172:173]
	v_pk_add_f32 v[126:127], v[126:127], v[166:167]
	v_pk_add_f32 v[128:129], v[128:129], v[168:169]
	v_pk_add_f32 v[130:131], v[130:131], v[170:171]
	v_pk_add_f32 v[132:133], v[132:133], v[172:173]
	v_pk_add_f32 v[134:135], v[134:135], v[166:167]
	v_pk_add_f32 v[136:137], v[136:137], v[168:169]
	v_pk_add_f32 v[138:139], v[138:139], v[170:171]
	v_pk_add_f32 v[140:141], v[140:141], v[172:173]
	v_pk_add_f32 v[142:143], v[142:143], v[166:167]
	v_pk_add_f32 v[144:145], v[144:145], v[168:169]
	v_pk_add_f32 v[146:147], v[146:147], v[170:171]
	v_pk_add_f32 v[148:149], v[148:149], v[172:173]
	v_pk_add_f32 v[150:151], v[150:151], v[166:167]
	v_pk_add_f32 v[152:153], v[152:153], v[168:169]
	v_pk_add_f32 v[154:155], v[154:155], v[170:171]
	v_pk_add_f32 v[156:157], v[156:157], v[172:173]
	v_pk_add_f32 v[158:159], v[158:159], v[166:167]
	v_pk_add_f32 v[160:161], v[160:161], v[168:169]
	v_pk_add_f32 v[162:163], v[162:163], v[170:171]
	v_pk_add_f32 v[164:165], v[164:165], v[172:173]
	v_lshlrev_b32_e32 v166, 16, v58
	v_and_b32_e32 v167, 0xffff0000, v58
	v_lshlrev_b32_e32 v168, 16, v59
	v_and_b32_e32 v169, 0xffff0000, v59
	v_lshlrev_b32_e32 v170, 16, v60
	v_and_b32_e32 v171, 0xffff0000, v60
	v_lshlrev_b32_e32 v172, 16, v61
	v_and_b32_e32 v173, 0xffff0000, v61
	v_pk_add_f32 v[110:111], v[110:111], v[166:167]
	v_pk_add_f32 v[112:113], v[112:113], v[168:169]
	v_pk_add_f32 v[114:115], v[114:115], v[170:171]
	v_pk_add_f32 v[116:117], v[116:117], v[172:173]
	v_pk_add_f32 v[118:119], v[118:119], v[166:167]
	v_pk_add_f32 v[120:121], v[120:121], v[168:169]
	v_pk_add_f32 v[122:123], v[122:123], v[170:171]
	v_pk_add_f32 v[124:125], v[124:125], v[172:173]
	v_pk_add_f32 v[126:127], v[126:127], v[166:167]
	v_pk_add_f32 v[128:129], v[128:129], v[168:169]
	v_pk_add_f32 v[130:131], v[130:131], v[170:171]
	v_pk_add_f32 v[132:133], v[132:133], v[172:173]
	v_pk_add_f32 v[134:135], v[134:135], v[166:167]
	v_pk_add_f32 v[136:137], v[136:137], v[168:169]
	v_pk_add_f32 v[138:139], v[138:139], v[170:171]
	v_pk_add_f32 v[140:141], v[140:141], v[172:173]
	v_pk_add_f32 v[142:143], v[142:143], v[166:167]
	v_pk_add_f32 v[144:145], v[144:145], v[168:169]
	v_pk_add_f32 v[146:147], v[146:147], v[170:171]
	v_pk_add_f32 v[148:149], v[148:149], v[172:173]
	v_pk_add_f32 v[150:151], v[150:151], v[166:167]
	v_pk_add_f32 v[152:153], v[152:153], v[168:169]
	v_pk_add_f32 v[154:155], v[154:155], v[170:171]
	v_pk_add_f32 v[156:157], v[156:157], v[172:173]
	v_pk_add_f32 v[158:159], v[158:159], v[166:167]
	v_pk_add_f32 v[160:161], v[160:161], v[168:169]
	v_pk_add_f32 v[162:163], v[162:163], v[170:171]
	v_pk_add_f32 v[164:165], v[164:165], v[172:173]
	v_lshlrev_b32_e32 v166, 16, v62
	v_and_b32_e32 v167, 0xffff0000, v62
	v_lshlrev_b32_e32 v168, 16, v63
	v_and_b32_e32 v169, 0xffff0000, v63
	v_lshlrev_b32_e32 v170, 16, v64
	v_and_b32_e32 v171, 0xffff0000, v64
	v_lshlrev_b32_e32 v172, 16, v65
	v_and_b32_e32 v173, 0xffff0000, v65
	v_pk_add_f32 v[118:119], v[118:119], v[166:167]
; #define GAS __attribute__((address_space(1)))
; __device__ __forceinline__ void prep_phase(Frame& F, CArgs a, int l, unsigned long long& tm_acc) {
;     ...
;             auto body = [&](auto WC) { constexpr int W = decltype(WC)::value;
;                 u32x4 v[W]; float mk[W];
; #pragma unroll
;                 for (int j = 0; j < W; ++j) { const int tt = t - W / 2 + j; const bool ok = tt >= 0 && tt < L; mk[j] = ok ? 1.f : 0.f; cnt += ok ? 1 : 0; v[j] = *(const GAS u32x4*)(zc + (size_t)(ok ? tt : t) * DIN); }
; #pragma unroll
;                 for (int j = 0; j < W; ++j) { s[0] += mk[j] * bflo(v[j].x); s[1] += mk[j] * bfhi(v[j].x); s[2] += mk[j] * bflo(v[j].y); s[3] += mk[j] * bfhi(v[j].y);
;                     s[4] += mk[j] * bflo(v[j].z); s[5] += mk[j] * bfhi(v[j].z); s[6] += mk[j] * bflo(v[j].w); s[7] += mk[j] * bfhi(v[j].w); } };
	v_pk_add_f32 v[120:121], v[120:121], v[168:169]
	v_pk_add_f32 v[122:123], v[122:123], v[170:171]
	v_pk_add_f32 v[124:125], v[124:125], v[172:173]
	v_pk_add_f32 v[126:127], v[126:127], v[166:167]
	v_pk_add_f32 v[128:129], v[128:129], v[168:169]
	v_pk_add_f32 v[130:131], v[130:131], v[170:171]
	v_pk_add_f32 v[132:133], v[132:133], v[172:173]
	v_pk_add_f32 v[134:135], v[134:135], v[166:167]
	v_pk_add_f32 v[136:137], v[136:137], v[168:169]
	v_pk_add_f32 v[138:139], v[138:139], v[170:171]
	v_pk_add_f32 v[140:141], v[140:141], v[172:173]
	v_pk_add_f32 v[142:143], v[142:143], v[166:167]
	v_pk_add_f32 v[144:145], v[144:145], v[168:169]
	v_pk_add_f32 v[146:147], v[146:147], v[170:171]
	v_pk_add_f32 v[148:149], v[148:149], v[172:173]
	v_pk_add_f32 v[150:151], v[150:151], v[166:167]
	v_pk_add_f32 v[152:153], v[152:153], v[168:169]
	v_pk_add_f32 v[154:155], v[154:155], v[170:171]
	v_pk_add_f32 v[156:157], v[156:157], v[172:173]
	v_pk_add_f32 v[158:159], v[158:159], v[166:167]
	v_pk_add_f32 v[160:161], v[160:161], v[168:169]
	v_pk_add_f32 v[162:163], v[162:163], v[170:171]
	v_pk_add_f32 v[164:165], v[164:165], v[172:173]
	v_lshlrev_b32_e32 v166, 16, v66
	v_and_b32_e32 v167, 0xffff0000, v66
	v_lshlrev_b32_e32 v168, 16, v67
	v_and_b32_e32 v169, 0xffff0000, v67
	v_lshlrev_b32_e32 v170, 16, v68
	v_and_b32_e32 v171, 0xffff0000, v68
	v_lshlrev_b32_e32 v172, 16, v69
	v_and_b32_e32 v173, 0xffff0000, v69
	v_pk_add_f32 v[126:127], v[126:127], v[166:167]
	v_pk_add_f32 v[128:129], v[128:129], v[168:169]
	v_pk_add_f32 v[130:131], v[130:131], v[170:171]
	v_pk_add_f32 v[132:133], v[132:133], v[172:173]
	v_pk_add_f32 v[134:135], v[134:135], v[166:167]
	v_pk_add_f32 v[136:137], v[136:137], v[168:169]
	v_pk_add_f32 v[138:139], v[138:139], v[170:171]
	v_pk_add_f32 v[140:141], v[140:141], v[172:173]
	v_pk_add_f32 v[142:143], v[142:143], v[166:167]
	v_pk_add_f32 v[144:145], v[144:145], v[168:169]
	v_pk_add_f32 v[146:147], v[146:147], v[170:171]
	v_pk_add_f32 v[148:149], v[148:149], v[172:173]
	v_pk_add_f32 v[150:151], v[150:151], v[166:167]
	v_pk_add_f32 v[152:153], v[152:153], v[168:169]
	v_pk_add_f32 v[154:155], v[154:155], v[170:171]
	v_pk_add_f32 v[156:157], v[156:157], v[172:173]
	v_pk_add_f32 v[158:159], v[158:159], v[166:167]
	v_pk_add_f32 v[160:161], v[160:161], v[168:169]
	v_pk_add_f32 v[162:163], v[162:163], v[170:171]
	v_pk_add_f32 v[164:165], v[164:165], v[172:173]
	v_lshlrev_b32_e32 v166, 16, v70
	v_and_b32_e32 v167, 0xffff0000, v70
	v_lshlrev_b32_e32 v168, 16, v71
	v_and_b32_e32 v169, 0xffff0000, v71
	v_lshlrev_b32_e32 v170, 16, v72
	v_and_b32_e32 v171, 0xffff0000, v72
	v_lshlrev_b32_e32 v172, 16, v73
	v_and_b32_e32 v173, 0xffff0000, v73
	v_pk_add_f32 v[134:135], v[134:135], v[166:167]
	v_pk_add_f32 v[136:137], v[136:137], v[168:169]
	v_pk_add_f32 v[138:139], v[138:139], v[170:171]
	v_pk_add_f32 v[140:141], v[140:141], v[172:173]
	v_pk_add_f32 v[142:143], v[142:143], v[166:167]
	v_pk_add_f32 v[144:145], v[144:145], v[168:169]
	v_pk_add_f32 v[146:147], v[146:147], v[170:171]
	v_pk_add_f32 v[148:149], v[148:149], v[172:173]
	v_pk_add_f32 v[150:151], v[150:151], v[166:167]
	v_pk_add_f32 v[152:153], v[152:153], v[168:169]
	v_pk_add_f32 v[154:155], v[154:155], v[170:171]
	v_pk_add_f32 v[156:157], v[156:157], v[172:173]
	v_pk_add_f32 v[158:159], v[158:159], v[166:167]
	v_pk_add_f32 v[160:161], v[160:161], v[168:169]
	v_pk_add_f32 v[162:163], v[162:163], v[170:171]
	v_pk_add_f32 v[164:165], v[164:165], v[172:173]
	v_lshlrev_b32_e32 v166, 16, v74
	v_and_b32_e32 v167, 0xffff0000, v74
	v_lshlrev_b32_e32 v168, 16, v75
	v_and_b32_e32 v169, 0xffff0000, v75
	v_lshlrev_b32_e32 v170, 16, v76
	v_and_b32_e32 v171, 0xffff0000, v76
	v_lshlrev_b32_e32 v172, 16, v77
	v_and_b32_e32 v173, 0xffff0000, v77
	v_pk_add_f32 v[142:143], v[142:143], v[166:167]
	v_pk_add_f32 v[144:145], v[144:145], v[168:169]
	v_pk_add_f32 v[146:147], v[146:147], v[170:171]
	v_pk_add_f32 v[148:149], v[148:149], v[172:173]
	v_pk_add_f32 v[150:151], v[150:151], v[166:167]
	v_pk_add_f32 v[152:153], v[152:153], v[168:169]
	v_pk_add_f32 v[154:155], v[154:155], v[170:171]
	v_pk_add_f32 v[156:157], v[156:157], v[172:173]
	v_pk_add_f32 v[158:159], v[158:159], v[166:167]
	v_pk_add_f32 v[160:161], v[160:161], v[168:169]
	v_pk_add_f32 v[162:163], v[162:163], v[170:171]
	v_pk_add_f32 v[164:165], v[164:165], v[172:173]
	v_lshlrev_b32_e32 v166, 16, v78
	v_and_b32_e32 v167, 0xffff0000, v78
	v_lshlrev_b32_e32 v168, 16, v79
	v_and_b32_e32 v169, 0xffff0000, v79
	v_lshlrev_b32_e32 v170, 16, v80
	v_and_b32_e32 v171, 0xffff0000, v80
	v_lshlrev_b32_e32 v172, 16, v81
	v_and_b32_e32 v173, 0xffff0000, v81
	v_pk_add_f32 v[150:151], v[150:151], v[166:167]
	v_pk_add_f32 v[152:153], v[152:153], v[168:169]
	v_pk_add_f32 v[154:155], v[154:155], v[170:171]
	v_pk_add_f32 v[156:157], v[156:157], v[172:173]
	v_pk_add_f32 v[158:159], v[158:159], v[166:167]
	v_pk_add_f32 v[160:161], v[160:161], v[168:169]
	v_pk_add_f32 v[162:163], v[162:163], v[170:171]
	v_pk_add_f32 v[164:165], v[164:165], v[172:173]
	v_lshlrev_b32_e32 v166, 16, v82
	v_and_b32_e32 v167, 0xffff0000, v82
	v_lshlrev_b32_e32 v168, 16, v83
	v_and_b32_e32 v169, 0xffff0000, v83
	v_lshlrev_b32_e32 v170, 16, v84
	v_and_b32_e32 v171, 0xffff0000, v84
	v_lshlrev_b32_e32 v172, 16, v85
	v_and_b32_e32 v173, 0xffff0000, v85
	v_pk_add_f32 v[158:159], v[158:159], v[166:167]
	v_pk_add_f32 v[160:161], v[160:161], v[168:169]
	v_pk_add_f32 v[162:163], v[162:163], v[170:171]
	v_pk_add_f32 v[164:165], v[164:165], v[172:173]
	s_branch .Lhp_fin
; #define GAS __attribute__((address_space(1)))
; __device__ __forceinline__ void prep_phase(Frame& F, CArgs a, int l, unsigned long long& tm_acc) {
;     ...
;             auto body = [&](auto WC) { constexpr int W = decltype(WC)::value;
;                 u32x4 v[W]; float mk[W];
; #pragma unroll
;                 for (int j = 0; j < W; ++j) { const int tt = t - W / 2 + j; const bool ok = tt >= 0 && tt < L; mk[j] = ok ? 1.f : 0.f; cnt += ok ? 1 : 0; v[j] = *(const GAS u32x4*)(zc + (size_t)(ok ? tt : t) * DIN); }
; #pragma unroll
;                 for (int j = 0; j < W; ++j) { s[0] += mk[j] * bflo(v[j].x); s[1] += mk[j] * bfhi(v[j].x); s[2] += mk[j] * bflo(v[j].y); s[3] += mk[j] * bfhi(v[j].y);
;                     s[4] += mk[j] * bflo(v[j].z); s[5] += mk[j] * bfhi(v[j].z); s[6] += mk[j] * bflo(v[j].w); s[7] += mk[j] * bfhi(v[j].w); } };
.Lhp_w1:
	v_add_u32_e32 v3, -2, v4
	v_mul_lo_u32 v2, v3, s22
	v_add_u32_e32 v2, v2, v5
	v_cmp_gt_u32_e64 s[18:19], s9, v3
	s_nop 1
	s_mov_b64 exec, s[18:19]
	global_load_dwordx4 v[34:37], v2, s[14:15]
	s_mov_b64 exec, -1
	v_add_u32_e32 v3, 1, v3
	v_add_u32_e32 v2, s22, v2
	v_cmp_gt_u32_e64 s[18:19], s9, v3
	s_nop 1
	s_mov_b64 exec, s[18:19]
	global_load_dwordx4 v[38:41], v2, s[14:15]
	s_mov_b64 exec, -1
	v_add_u32_e32 v3, 1, v3
	v_add_u32_e32 v2, s22, v2
	v_cmp_gt_u32_e64 s[18:19], s9, v3
	s_nop 1
	s_mov_b64 exec, s[18:19]
	global_load_dwordx4 v[42:45], v2, s[14:15]
	s_mov_b64 exec, -1
	v_add_u32_e32 v3, 1, v3
	v_add_u32_e32 v2, s22, v2
	v_cmp_gt_u32_e64 s[18:19], s9, v3
	s_nop 1
	s_mov_b64 exec, s[18:19]
	global_load_dwordx4 v[46:49], v2, s[14:15]
	s_mov_b64 exec, -1
	v_add_u32_e32 v3, 1, v3
	v_add_u32_e32 v2, s22, v2
	v_cmp_gt_u32_e64 s[18:19], s9, v3
	s_nop 1
	s_mov_b64 exec, s[18:19]
	global_load_dwordx4 v[50:53], v2, s[14:15]
	s_mov_b64 exec, -1
	v_add_u32_e32 v3, 1, v3
	v_add_u32_e32 v2, s22, v2
	v_cmp_gt_u32_e64 s[18:19], s9, v3
	s_nop 1
	s_mov_b64 exec, s[18:19]
	global_load_dwordx4 v[54:57], v2, s[14:15]
	s_mov_b64 exec, -1
	v_add_u32_e32 v3, 1, v3
	v_add_u32_e32 v2, s22, v2
	v_cmp_gt_u32_e64 s[18:19], s9, v3
	s_nop 1
	s_mov_b64 exec, s[18:19]
	global_load_dwordx4 v[58:61], v2, s[14:15]
	s_mov_b64 exec, -1
	v_add_u32_e32 v3, 1, v3
	v_add_u32_e32 v2, s22, v2
	v_cmp_gt_u32_e64 s[18:19], s9, v3
	s_nop 1
	s_mov_b64 exec, s[18:19]
	global_load_dwordx4 v[62:65], v2, s[14:15]
	s_mov_b64 exec, -1
	v_add_u32_e32 v3, 1, v3
	v_add_u32_e32 v2, s22, v2
	v_cmp_gt_u32_e64 s[18:19], s9, v3
	s_nop 1
	s_mov_b64 exec, s[18:19]
	global_load_dwordx4 v[66:69], v2, s[14:15]
	s_mov_b64 exec, -1
	v_add_u32_e32 v3, 1, v3
	v_add_u32_e32 v2, s22, v2
	v_cmp_gt_u32_e64 s[18:19], s9, v3
	s_nop 1
	s_mov_b64 exec, s[18:19]
	global_load_dwordx4 v[70:73], v2, s[14:15]
	s_mov_b64 exec, -1
	v_add_u32_e32 v3, 1, v3
	v_add_u32_e32 v2, s22, v2
	v_cmp_gt_u32_e64 s[18:19], s9, v3
	s_nop 1
	s_mov_b64 exec, s[18:19]
	global_load_dwordx4 v[74:77], v2, s[14:15]
	s_mov_b64 exec, -1
	s_waitcnt vmcnt(0)
	v_lshlrev_b32_e32 v166, 16, v34
	v_and_b32_e32 v167, 0xffff0000, v34
	v_lshlrev_b32_e32 v168, 16, v35
	v_and_b32_e32 v169, 0xffff0000, v35
	v_lshlrev_b32_e32 v170, 16, v36
	v_and_b32_e32 v171, 0xffff0000, v36
	v_lshlrev_b32_e32 v172, 16, v37
	v_and_b32_e32 v173, 0xffff0000, v37
	v_pk_add_f32 v[102:103], v[102:103], v[166:167]
	v_pk_add_f32 v[104:105], v[104:105], v[168:169]
	v_pk_add_f32 v[106:107], v[106:107], v[170:171]
	v_pk_add_f32 v[108:109], v[108:109], v[172:173]
	v_lshlrev_b32_e32 v166, 16, v38
	v_and_b32_e32 v167, 0xffff0000, v38
	v_lshlrev_b32_e32 v168, 16, v39
	v_and_b32_e32 v169, 0xffff0000, v39
	v_lshlrev_b32_e32 v170, 16, v40
	v_and_b32_e32 v171, 0xffff0000, v40
	v_lshlrev_b32_e32 v172, 16, v41
	v_and_b32_e32 v173, 0xffff0000, v41
	v_pk_add_f32 v[102:103], v[102:103], v[166:167]
	v_pk_add_f32 v[104:105], v[104:105], v[168:169]
	v_pk_add_f32 v[106:107], v[106:107], v[170:171]
	v_pk_add_f32 v[108:109], v[108:109], v[172:173]
	v_pk_add_f32 v[110:111], v[110:111], v[166:167]
	v_pk_add_f32 v[112:113], v[112:113], v[168:169]
	v_pk_add_f32 v[114:115], v[114:115], v[170:171]
	v_pk_add_f32 v[116:117], v[116:117], v[172:173]
	v_lshlrev_b32_e32 v166, 16, v42
	v_and_b32_e32 v167, 0xffff0000, v42
	v_lshlrev_b32_e32 v168, 16, v43
	v_and_b32_e32 v169, 0xffff0000, v43
	v_lshlrev_b32_e32 v170, 16, v44
	v_and_b32_e32 v171, 0xffff0000, v44
	v_lshlrev_b32_e32 v172, 16, v45
	v_and_b32_e32 v173, 0xffff0000, v45
	v_pk_add_f32 v[102:103], v[102:103], v[166:167]
	v_pk_add_f32 v[104:105], v[104:105], v[168:169]
	v_pk_add_f32 v[106:107], v[106:107], v[170:171]
	v_pk_add_f32 v[108:109], v[108:109], v[172:173]
	v_pk_add_f32 v[110:111], v[110:111], v[166:167]
	v_pk_add_f32 v[112:113], v[112:113], v[168:169]
	v_pk_add_f32 v[114:115], v[114:115], v[170:171]
	v_pk_add_f32 v[116:117], v[116:117], v[172:173]
	v_pk_add_f32 v[118:119], v[118:119], v[166:167]
	v_pk_add_f32 v[120:121], v[120:121], v[168:169]
	v_pk_add_f32 v[122:123], v[122:123], v[170:171]
	v_pk_add_f32 v[124:125], v[124:125], v[172:173]
	v_lshlrev_b32_e32 v166, 16, v46
	v_and_b32_e32 v167, 0xffff0000, v46
	v_lshlrev_b32_e32 v168, 16, v47
	v_and_b32_e32 v169, 0xffff0000, v47
	v_lshlrev_b32_e32 v170, 16, v48
	v_and_b32_e32 v171, 0xffff0000, v48
	v_lshlrev_b32_e32 v172, 16, v49
	v_and_b32_e32 v173, 0xffff0000, v49
	v_pk_add_f32 v[102:103], v[102:103], v[166:167]
	v_pk_add_f32 v[104:105], v[104:105], v[168:169]
	v_pk_add_f32 v[106:107], v[106:107], v[170:171]
	v_pk_add_f32 v[108:109], v[108:109], v[172:173]
	v_pk_add_f32 v[110:111], v[110:111], v[166:167]
	v_pk_add_f32 v[112:113], v[112:113], v[168:169]
	v_pk_add_f32 v[114:115], v[114:115], v[170:171]
	v_pk_add_f32 v[116:117], v[116:117], v[172:173]
	v_pk_add_f32 v[118:119], v[118:119], v[166:167]
	v_pk_add_f32 v[120:121], v[120:121], v[168:169]
	v_pk_add_f32 v[122:123], v[122:123], v[170:171]
	v_pk_add_f32 v[124:125], v[124:125], v[172:173]
	v_pk_add_f32 v[126:127], v[126:127], v[166:167]
	v_pk_add_f32 v[128:129], v[128:129], v[168:169]
	v_pk_add_f32 v[130:131], v[130:131], v[170:171]
	v_pk_add_f32 v[132:133], v[132:133], v[172:173]
	v_lshlrev_b32_e32 v166, 16, v50
	v_and_b32_e32 v167, 0xffff0000, v50
	v_lshlrev_b32_e32 v168, 16, v51
	v_and_b32_e32 v169, 0xffff0000, v51
	v_lshlrev_b32_e32 v170, 16, v52
	v_and_b32_e32 v171, 0xffff0000, v52
	v_lshlrev_b32_e32 v172, 16, v53
	v_and_b32_e32 v173, 0xffff0000, v53
	v_pk_add_f32 v[110:111], v[110:111], v[166:167]
	v_pk_add_f32 v[112:113], v[112:113], v[168:169]
	v_pk_add_f32 v[114:115], v[114:115], v[170:171]
	v_pk_add_f32 v[116:117], v[116:117], v[172:173]
; #define GAS __attribute__((address_space(1)))
; __device__ __forceinline__ void prep_phase(Frame& F, CArgs a, int l, unsigned long long& tm_acc) {
;     ...
;             auto body = [&](auto WC) { constexpr int W = decltype(WC)::value;
;                 u32x4 v[W]; float mk[W];
; #pragma unroll
;                 for (int j = 0; j < W; ++j) { const int tt = t - W / 2 + j; const bool ok = tt >= 0 && tt < L; mk[j] = ok ? 1.f : 0.f; cnt += ok ? 1 : 0; v[j] = *(const GAS u32x4*)(zc + (size_t)(ok ? tt : t) * DIN); }
; #pragma unroll
;                 for (int j = 0; j < W; ++j) { s[0] += mk[j] * bflo(v[j].x); s[1] += mk[j] * bfhi(v[j].x); s[2] += mk[j] * bflo(v[j].y); s[3] += mk[j] * bfhi(v[j].y);
;                     s[4] += mk[j] * bflo(v[j].z); s[5] += mk[j] * bfhi(v[j].z); s[6] += mk[j] * bflo(v[j].w); s[7] += mk[j] * bfhi(v[j].w); } };
	v_pk_add_f32 v[118:119], v[118:119], v[166:167]
	v_pk_add_f32 v[120:121], v[120:121], v[168:169]
	v_pk_add_f32 v[122:123], v[122:123], v[170:171]
	v_pk_add_f32 v[124:125], v[124:125], v[172:173]
	v_pk_add_f32 v[126:127], v[126:127], v[166:167]
	v_pk_add_f32 v[128:129], v[128:129], v[168:169]
	v_pk_add_f32 v[130:131], v[130:131], v[170:171]
	v_pk_add_f32 v[132:133], v[132:133], v[172:173]
	v_pk_add_f32 v[134:135], v[134:135], v[166:167]
	v_pk_add_f32 v[136:137], v[136:137], v[168:169]
	v_pk_add_f32 v[138:139], v[138:139], v[170:171]
	v_pk_add_f32 v[140:141], v[140:141], v[172:173]
	v_lshlrev_b32_e32 v166, 16, v54
	v_and_b32_e32 v167, 0xffff0000, v54
	v_lshlrev_b32_e32 v168, 16, v55
	v_and_b32_e32 v169, 0xffff0000, v55
	v_lshlrev_b32_e32 v170, 16, v56
	v_and_b32_e32 v171, 0xffff0000, v56
	v_lshlrev_b32_e32 v172, 16, v57
	v_and_b32_e32 v173, 0xffff0000, v57
	v_pk_add_f32 v[118:119], v[118:119], v[166:167]
	v_pk_add_f32 v[120:121], v[120:121], v[168:169]
	v_pk_add_f32 v[122:123], v[122:123], v[170:171]
	v_pk_add_f32 v[124:125], v[124:125], v[172:173]
	v_pk_add_f32 v[126:127], v[126:127], v[166:167]
	v_pk_add_f32 v[128:129], v[128:129], v[168:169]
	v_pk_add_f32 v[130:131], v[130:131], v[170:171]
	v_pk_add_f32 v[132:133], v[132:133], v[172:173]
	v_pk_add_f32 v[134:135], v[134:135], v[166:167]
	v_pk_add_f32 v[136:137], v[136:137], v[168:169]
	v_pk_add_f32 v[138:139], v[138:139], v[170:171]
	v_pk_add_f32 v[140:141], v[140:141], v[172:173]
	v_pk_add_f32 v[142:143], v[142:143], v[166:167]
	v_pk_add_f32 v[144:145], v[144:145], v[168:169]
	v_pk_add_f32 v[146:147], v[146:147], v[170:171]
	v_pk_add_f32 v[148:149], v[148:149], v[172:173]
	v_lshlrev_b32_e32 v166, 16, v58
	v_and_b32_e32 v167, 0xffff0000, v58
	v_lshlrev_b32_e32 v168, 16, v59
	v_and_b32_e32 v169, 0xffff0000, v59
	v_lshlrev_b32_e32 v170, 16, v60
	v_and_b32_e32 v171, 0xffff0000, v60
	v_lshlrev_b32_e32 v172, 16, v61
	v_and_b32_e32 v173, 0xffff0000, v61
	v_pk_add_f32 v[126:127], v[126:127], v[166:167]
	v_pk_add_f32 v[128:129], v[128:129], v[168:169]
	v_pk_add_f32 v[130:131], v[130:131], v[170:171]
	v_pk_add_f32 v[132:133], v[132:133], v[172:173]
	v_pk_add_f32 v[134:135], v[134:135], v[166:167]
	v_pk_add_f32 v[136:137], v[136:137], v[168:169]
	v_pk_add_f32 v[138:139], v[138:139], v[170:171]
	v_pk_add_f32 v[140:141], v[140:141], v[172:173]
	v_pk_add_f32 v[142:143], v[142:143], v[166:167]
	v_pk_add_f32 v[144:145], v[144:145], v[168:169]
	v_pk_add_f32 v[146:147], v[146:147], v[170:171]
	v_pk_add_f32 v[148:149], v[148:149], v[172:173]
	v_pk_add_f32 v[150:151], v[150:151], v[166:167]
	v_pk_add_f32 v[152:153], v[152:153], v[168:169]
	v_pk_add_f32 v[154:155], v[154:155], v[170:171]
	v_pk_add_f32 v[156:157], v[156:157], v[172:173]
	v_lshlrev_b32_e32 v166, 16, v62
	v_and_b32_e32 v167, 0xffff0000, v62
	v_lshlrev_b32_e32 v168, 16, v63
	v_and_b32_e32 v169, 0xffff0000, v63
	v_lshlrev_b32_e32 v170, 16, v64
	v_and_b32_e32 v171, 0xffff0000, v64
	v_lshlrev_b32_e32 v172, 16, v65
	v_and_b32_e32 v173, 0xffff0000, v65
	v_pk_add_f32 v[134:135], v[134:135], v[166:167]
	v_pk_add_f32 v[136:137], v[136:137], v[168:169]
	v_pk_add_f32 v[138:139], v[138:139], v[170:171]
	v_pk_add_f32 v[140:141], v[140:141], v[172:173]
	v_pk_add_f32 v[142:143], v[142:143], v[166:167]
	v_pk_add_f32 v[144:145], v[144:145], v[168:169]
	v_pk_add_f32 v[146:147], v[146:147], v[170:171]
	v_pk_add_f32 v[148:149], v[148:149], v[172:173]
	v_pk_add_f32 v[150:151], v[150:151], v[166:167]
	v_pk_add_f32 v[152:153], v[152:153], v[168:169]
	v_pk_add_f32 v[154:155], v[154:155], v[170:171]
	v_pk_add_f32 v[156:157], v[156:157], v[172:173]
	v_pk_add_f32 v[158:159], v[158:159], v[166:167]
	v_pk_add_f32 v[160:161], v[160:161], v[168:169]
	v_pk_add_f32 v[162:163], v[162:163], v[170:171]
	v_pk_add_f32 v[164:165], v[164:165], v[172:173]
	v_lshlrev_b32_e32 v166, 16, v66
	v_and_b32_e32 v167, 0xffff0000, v66
	v_lshlrev_b32_e32 v168, 16, v67
	v_and_b32_e32 v169, 0xffff0000, v67
	v_lshlrev_b32_e32 v170, 16, v68
	v_and_b32_e32 v171, 0xffff0000, v68
	v_lshlrev_b32_e32 v172, 16, v69
	v_and_b32_e32 v173, 0xffff0000, v69
	v_pk_add_f32 v[142:143], v[142:143], v[166:167]
	v_pk_add_f32 v[144:145], v[144:145], v[168:169]
	v_pk_add_f32 v[146:147], v[146:147], v[170:171]
	v_pk_add_f32 v[148:149], v[148:149], v[172:173]
	v_pk_add_f32 v[150:151], v[150:151], v[166:167]
	v_pk_add_f32 v[152:153], v[152:153], v[168:169]
	v_pk_add_f32 v[154:155], v[154:155], v[170:171]
	v_pk_add_f32 v[156:157], v[156:157], v[172:173]
	v_pk_add_f32 v[158:159], v[158:159], v[166:167]
	v_pk_add_f32 v[160:161], v[160:161], v[168:169]
	v_pk_add_f32 v[162:163], v[162:163], v[170:171]
	v_pk_add_f32 v[164:165], v[164:165], v[172:173]
	v_lshlrev_b32_e32 v166, 16, v70
	v_and_b32_e32 v167, 0xffff0000, v70
	v_lshlrev_b32_e32 v168, 16, v71
	v_and_b32_e32 v169, 0xffff0000, v71
	v_lshlrev_b32_e32 v170, 16, v72
	v_and_b32_e32 v171, 0xffff0000, v72
	v_lshlrev_b32_e32 v172, 16, v73
	v_and_b32_e32 v173, 0xffff0000, v73
	v_pk_add_f32 v[150:151], v[150:151], v[166:167]
	v_pk_add_f32 v[152:153], v[152:153], v[168:169]
	v_pk_add_f32 v[154:155], v[154:155], v[170:171]
	v_pk_add_f32 v[156:157], v[156:157], v[172:173]
	v_pk_add_f32 v[158:159], v[158:159], v[166:167]
	v_pk_add_f32 v[160:161], v[160:161], v[168:169]
	v_pk_add_f32 v[162:163], v[162:163], v[170:171]
	v_pk_add_f32 v[164:165], v[164:165], v[172:173]
	v_lshlrev_b32_e32 v166, 16, v74
	v_and_b32_e32 v167, 0xffff0000, v74
	v_lshlrev_b32_e32 v168, 16, v75
	v_and_b32_e32 v169, 0xffff0000, v75
	v_lshlrev_b32_e32 v170, 16, v76
	v_and_b32_e32 v171, 0xffff0000, v76
	v_lshlrev_b32_e32 v172, 16, v77
	v_and_b32_e32 v173, 0xffff0000, v77
	v_pk_add_f32 v[158:159], v[158:159], v[166:167]
	v_pk_add_f32 v[160:161], v[160:161], v[168:169]
	v_pk_add_f32 v[162:163], v[162:163], v[170:171]
	v_pk_add_f32 v[164:165], v[164:165], v[172:173]
	s_branch .Lhp_fin
; #define GAS __attribute__((address_space(1)))
; __device__ __forceinline__ void prep_phase(Frame& F, CArgs a, int l, unsigned long long& tm_acc) {
;     ...
;             auto body = [&](auto WC) { constexpr int W = decltype(WC)::value;
;                 u32x4 v[W]; float mk[W];
; #pragma unroll
;                 for (int j = 0; j < W; ++j) { const int tt = t - W / 2 + j; const bool ok = tt >= 0 && tt < L; mk[j] = ok ? 1.f : 0.f; cnt += ok ? 1 : 0; v[j] = *(const GAS u32x4*)(zc + (size_t)(ok ? tt : t) * DIN); }
; #pragma unroll
;                 for (int j = 0; j < W; ++j) { s[0] += mk[j] * bflo(v[j].x); s[1] += mk[j] * bfhi(v[j].x); s[2] += mk[j] * bflo(v[j].y); s[3] += mk[j] * bfhi(v[j].y);
;                     s[4] += mk[j] * bflo(v[j].z); s[5] += mk[j] * bfhi(v[j].z); s[6] += mk[j] * bflo(v[j].w); s[7] += mk[j] * bfhi(v[j].w); } };
.Lhp_w0:
	v_add_u32_e32 v3, -1, v4
	v_mul_lo_u32 v2, v3, s22
	v_add_u32_e32 v2, v2, v5
	v_cmp_gt_u32_e64 s[18:19], s9, v3
	s_nop 1
	s_mov_b64 exec, s[18:19]
	global_load_dwordx4 v[38:41], v2, s[14:15]
	s_mov_b64 exec, -1
	v_add_u32_e32 v3, 1, v3
	v_add_u32_e32 v2, s22, v2
	v_cmp_gt_u32_e64 s[18:19], s9, v3
	s_nop 1
	s_mov_b64 exec, s[18:19]
	global_load_dwordx4 v[42:45], v2, s[14:15]
	s_mov_b64 exec, -1
	v_add_u32_e32 v3, 1, v3
	v_add_u32_e32 v2, s22, v2
	v_cmp_gt_u32_e64 s[18:19], s9, v3
	s_nop 1
	s_mov_b64 exec, s[18:19]
	global_load_dwordx4 v[46:49], v2, s[14:15]
	s_mov_b64 exec, -1
	v_add_u32_e32 v3, 1, v3
	v_add_u32_e32 v2, s22, v2
	v_cmp_gt_u32_e64 s[18:19], s9, v3
	s_nop 1
	s_mov_b64 exec, s[18:19]
	global_load_dwordx4 v[50:53], v2, s[14:15]
	s_mov_b64 exec, -1
	v_add_u32_e32 v3, 1, v3
	v_add_u32_e32 v2, s22, v2
	v_cmp_gt_u32_e64 s[18:19], s9, v3
	s_nop 1
	s_mov_b64 exec, s[18:19]
	global_load_dwordx4 v[54:57], v2, s[14:15]
	s_mov_b64 exec, -1
	v_add_u32_e32 v3, 1, v3
	v_add_u32_e32 v2, s22, v2
	v_cmp_gt_u32_e64 s[18:19], s9, v3
	s_nop 1
	s_mov_b64 exec, s[18:19]
	global_load_dwordx4 v[58:61], v2, s[14:15]
	s_mov_b64 exec, -1
	v_add_u32_e32 v3, 1, v3
	v_add_u32_e32 v2, s22, v2
	v_cmp_gt_u32_e64 s[18:19], s9, v3
	s_nop 1
	s_mov_b64 exec, s[18:19]
	global_load_dwordx4 v[62:65], v2, s[14:15]
	s_mov_b64 exec, -1
	v_add_u32_e32 v3, 1, v3
	v_add_u32_e32 v2, s22, v2
	v_cmp_gt_u32_e64 s[18:19], s9, v3
	s_nop 1
	s_mov_b64 exec, s[18:19]
	global_load_dwordx4 v[66:69], v2, s[14:15]
	s_mov_b64 exec, -1
	v_add_u32_e32 v3, 1, v3
	v_add_u32_e32 v2, s22, v2
	v_cmp_gt_u32_e64 s[18:19], s9, v3
	s_nop 1
	s_mov_b64 exec, s[18:19]
	global_load_dwordx4 v[70:73], v2, s[14:15]
	s_mov_b64 exec, -1
	s_waitcnt vmcnt(0)
	v_lshlrev_b32_e32 v166, 16, v38
	v_and_b32_e32 v167, 0xffff0000, v38
	v_lshlrev_b32_e32 v168, 16, v39
	v_and_b32_e32 v169, 0xffff0000, v39
	v_lshlrev_b32_e32 v170, 16, v40
	v_and_b32_e32 v171, 0xffff0000, v40
	v_lshlrev_b32_e32 v172, 16, v41
	v_and_b32_e32 v173, 0xffff0000, v41
	v_pk_add_f32 v[102:103], v[102:103], v[166:167]
	v_pk_add_f32 v[104:105], v[104:105], v[168:169]
	v_pk_add_f32 v[106:107], v[106:107], v[170:171]
	v_pk_add_f32 v[108:109], v[108:109], v[172:173]
	v_lshlrev_b32_e32 v166, 16, v42
	v_and_b32_e32 v167, 0xffff0000, v42
	v_lshlrev_b32_e32 v168, 16, v43
	v_and_b32_e32 v169, 0xffff0000, v43
	v_lshlrev_b32_e32 v170, 16, v44
	v_and_b32_e32 v171, 0xffff0000, v44
	v_lshlrev_b32_e32 v172, 16, v45
	v_and_b32_e32 v173, 0xffff0000, v45
	v_pk_add_f32 v[102:103], v[102:103], v[166:167]
	v_pk_add_f32 v[104:105], v[104:105], v[168:169]
	v_pk_add_f32 v[106:107], v[106:107], v[170:171]
	v_pk_add_f32 v[108:109], v[108:109], v[172:173]
	v_pk_add_f32 v[110:111], v[110:111], v[166:167]
	v_pk_add_f32 v[112:113], v[112:113], v[168:169]
	v_pk_add_f32 v[114:115], v[114:115], v[170:171]
	v_pk_add_f32 v[116:117], v[116:117], v[172:173]
	v_lshlrev_b32_e32 v166, 16, v46
	v_and_b32_e32 v167, 0xffff0000, v46
	v_lshlrev_b32_e32 v168, 16, v47
	v_and_b32_e32 v169, 0xffff0000, v47
	v_lshlrev_b32_e32 v170, 16, v48
	v_and_b32_e32 v171, 0xffff0000, v48
	v_lshlrev_b32_e32 v172, 16, v49
	v_and_b32_e32 v173, 0xffff0000, v49
	v_pk_add_f32 v[110:111], v[110:111], v[166:167]
	v_pk_add_f32 v[112:113], v[112:113], v[168:169]
	v_pk_add_f32 v[114:115], v[114:115], v[170:171]
	v_pk_add_f32 v[116:117], v[116:117], v[172:173]
	v_pk_add_f32 v[118:119], v[118:119], v[166:167]
	v_pk_add_f32 v[120:121], v[120:121], v[168:169]
	v_pk_add_f32 v[122:123], v[122:123], v[170:171]
	v_pk_add_f32 v[124:125], v[124:125], v[172:173]
	v_lshlrev_b32_e32 v166, 16, v50
	v_and_b32_e32 v167, 0xffff0000, v50
	v_lshlrev_b32_e32 v168, 16, v51
	v_and_b32_e32 v169, 0xffff0000, v51
	v_lshlrev_b32_e32 v170, 16, v52
	v_and_b32_e32 v171, 0xffff0000, v52
	v_lshlrev_b32_e32 v172, 16, v53
	v_and_b32_e32 v173, 0xffff0000, v53
	v_pk_add_f32 v[118:119], v[118:119], v[166:167]
	v_pk_add_f32 v[120:121], v[120:121], v[168:169]
	v_pk_add_f32 v[122:123], v[122:123], v[170:171]
	v_pk_add_f32 v[124:125], v[124:125], v[172:173]
	v_pk_add_f32 v[126:127], v[126:127], v[166:167]
	v_pk_add_f32 v[128:129], v[128:129], v[168:169]
	v_pk_add_f32 v[130:131], v[130:131], v[170:171]
	v_pk_add_f32 v[132:133], v[132:133], v[172:173]
	v_lshlrev_b32_e32 v166, 16, v54
	v_and_b32_e32 v167, 0xffff0000, v54
	v_lshlrev_b32_e32 v168, 16, v55
	v_and_b32_e32 v169, 0xffff0000, v55
	v_lshlrev_b32_e32 v170, 16, v56
	v_and_b32_e32 v171, 0xffff0000, v56
	v_lshlrev_b32_e32 v172, 16, v57
	v_and_b32_e32 v173, 0xffff0000, v57
	v_pk_add_f32 v[126:127], v[126:127], v[166:167]
	v_pk_add_f32 v[128:129], v[128:129], v[168:169]
	v_pk_add_f32 v[130:131], v[130:131], v[170:171]
	v_pk_add_f32 v[132:133], v[132:133], v[172:173]
	v_pk_add_f32 v[134:135], v[134:135], v[166:167]
	v_pk_add_f32 v[136:137], v[136:137], v[168:169]
	v_pk_add_f32 v[138:139], v[138:139], v[170:171]
	v_pk_add_f32 v[140:141], v[140:141], v[172:173]
	v_lshlrev_b32_e32 v166, 16, v58
	v_and_b32_e32 v167, 0xffff0000, v58
	v_lshlrev_b32_e32 v168, 16, v59
	v_and_b32_e32 v169, 0xffff0000, v59
	v_lshlrev_b32_e32 v170, 16, v60
	v_and_b32_e32 v171, 0xffff0000, v60
	v_lshlrev_b32_e32 v172, 16, v61
	v_and_b32_e32 v173, 0xffff0000, v61
	v_pk_add_f32 v[134:135], v[134:135], v[166:167]
	v_pk_add_f32 v[136:137], v[136:137], v[168:169]
	v_pk_add_f32 v[138:139], v[138:139], v[170:171]
	v_pk_add_f32 v[140:141], v[140:141], v[172:173]
	v_pk_add_f32 v[142:143], v[142:143], v[166:167]
	v_pk_add_f32 v[144:145], v[144:145], v[168:169]
	v_pk_add_f32 v[146:147], v[146:147], v[170:171]
	v_pk_add_f32 v[148:149], v[148:149], v[172:173]
	v_lshlrev_b32_e32 v166, 16, v62
	v_and_b32_e32 v167, 0xffff0000, v62
; #define GAS __attribute__((address_space(1)))
; __device__ __forceinline__ unsigned pk2(float lo, float hi) { unsigned r; asm("v_cvt_pk_bf16_f32 %0, %1, %2" : "=v"(r) : "v"(lo), "v"(hi)); return r; }
; __device__ __forceinline__ void prep_phase(Frame& F, CArgs a, int l, unsigned long long& tm_acc) {
;     ...
;             const u32x4 sv = *(const GAS u32x4*)(zc + (size_t)t * DIN);
;             const float inv = 1.0f / (float)cnt;
;             u32x4 o; o.x = pk2(s[0] * inv - bflo(sv.x), s[1] * inv - bfhi(sv.x)); o.y = pk2(s[2] * inv - bflo(sv.y), s[3] * inv - bfhi(sv.y));
;             o.z = pk2(s[4] * inv - bflo(sv.z), s[5] * inv - bfhi(sv.z)); o.w = pk2(s[6] * inv - bflo(sv.w), s[7] * inv - bfhi(sv.w));
;             *(GAS u32x4*)(P + (size_t)row * 512 + cg * 8) = o;
	v_lshlrev_b32_e32 v168, 16, v63
	v_and_b32_e32 v169, 0xffff0000, v63
	v_lshlrev_b32_e32 v170, 16, v64
	v_and_b32_e32 v171, 0xffff0000, v64
	v_lshlrev_b32_e32 v172, 16, v65
	v_and_b32_e32 v173, 0xffff0000, v65
	v_pk_add_f32 v[142:143], v[142:143], v[166:167]
	v_pk_add_f32 v[144:145], v[144:145], v[168:169]
	v_pk_add_f32 v[146:147], v[146:147], v[170:171]
	v_pk_add_f32 v[148:149], v[148:149], v[172:173]
	v_pk_add_f32 v[150:151], v[150:151], v[166:167]
	v_pk_add_f32 v[152:153], v[152:153], v[168:169]
	v_pk_add_f32 v[154:155], v[154:155], v[170:171]
	v_pk_add_f32 v[156:157], v[156:157], v[172:173]
	v_lshlrev_b32_e32 v166, 16, v66
	v_and_b32_e32 v167, 0xffff0000, v66
	v_lshlrev_b32_e32 v168, 16, v67
	v_and_b32_e32 v169, 0xffff0000, v67
	v_lshlrev_b32_e32 v170, 16, v68
	v_and_b32_e32 v171, 0xffff0000, v68
	v_lshlrev_b32_e32 v172, 16, v69
	v_and_b32_e32 v173, 0xffff0000, v69
	v_pk_add_f32 v[150:151], v[150:151], v[166:167]
	v_pk_add_f32 v[152:153], v[152:153], v[168:169]
	v_pk_add_f32 v[154:155], v[154:155], v[170:171]
	v_pk_add_f32 v[156:157], v[156:157], v[172:173]
	v_pk_add_f32 v[158:159], v[158:159], v[166:167]
	v_pk_add_f32 v[160:161], v[160:161], v[168:169]
	v_pk_add_f32 v[162:163], v[162:163], v[170:171]
	v_pk_add_f32 v[164:165], v[164:165], v[172:173]
	v_lshlrev_b32_e32 v166, 16, v70
	v_and_b32_e32 v167, 0xffff0000, v70
	v_lshlrev_b32_e32 v168, 16, v71
	v_and_b32_e32 v169, 0xffff0000, v71
	v_lshlrev_b32_e32 v170, 16, v72
	v_and_b32_e32 v171, 0xffff0000, v72
	v_lshlrev_b32_e32 v172, 16, v73
	v_and_b32_e32 v173, 0xffff0000, v73
	v_pk_add_f32 v[158:159], v[158:159], v[166:167]
	v_pk_add_f32 v[160:161], v[160:161], v[168:169]
	v_pk_add_f32 v[162:163], v[162:163], v[170:171]
	v_pk_add_f32 v[164:165], v[164:165], v[172:173]
.Lhp_fin:
	v_add_u32_e32 v174, 0, v4
	v_subrev_u32_e32 v175, s6, v174
	v_max_i32_e32 v175, 0, v175
	v_add_u32_e32 v176, s6, v174
	v_min_i32_e32 v176, s9, v176
	v_sub_u32_e32 v176, v176, v175
	v_cvt_f32_u32_e32 v177, v176
	v_div_scale_f32 v178, s[18:19], v177, v177, 1.0
	v_rcp_f32_e32 v179, v178
	s_nop 0
	v_fma_f32 v180, -v178, v179, 1.0
	v_fmac_f32_e32 v179, v180, v179
	v_div_scale_f32 v180, vcc, 1.0, v177, 1.0
	v_mul_f32_e32 v181, v180, v179
	v_fma_f32 v182, -v178, v181, v180
	v_fmac_f32_e32 v181, v182, v179
	v_fma_f32 v178, -v178, v181, v180
	v_div_fmas_f32 v178, v178, v179, v181
	v_div_fixup_f32 v179, v178, v177, 1.0
	v_lshlrev_b32_e32 v166, 16, v42
	v_and_b32_e32 v167, 0xffff0000, v42
	v_lshlrev_b32_e32 v168, 16, v43
	v_and_b32_e32 v169, 0xffff0000, v43
	v_lshlrev_b32_e32 v170, 16, v44
	v_and_b32_e32 v171, 0xffff0000, v44
	v_lshlrev_b32_e32 v172, 16, v45
	v_and_b32_e32 v173, 0xffff0000, v45
	v_fma_f32 v102, v102, v179, -v166
	v_fma_f32 v103, v103, v179, -v167
	v_fma_f32 v104, v104, v179, -v168
	v_fma_f32 v105, v105, v179, -v169
	v_fma_f32 v106, v106, v179, -v170
	v_fma_f32 v107, v107, v179, -v171
	v_fma_f32 v108, v108, v179, -v172
	v_fma_f32 v109, v109, v179, -v173
	v_cvt_pk_bf16_f32 v184, v102, v103
	v_cvt_pk_bf16_f32 v185, v104, v105
	v_cvt_pk_bf16_f32 v186, v106, v107
	v_cvt_pk_bf16_f32 v187, v108, v109
	v_lshl_add_u32 v183, v174, 10, v5
	global_store_dwordx4 v183, v[184:187], s[16:17]
	s_nop 1
	v_add_u32_e32 v174, 1, v4
	v_subrev_u32_e32 v175, s6, v174
	v_max_i32_e32 v175, 0, v175
	v_add_u32_e32 v176, s6, v174
	v_min_i32_e32 v176, s9, v176
	v_sub_u32_e32 v176, v176, v175
	v_cvt_f32_u32_e32 v177, v176
	v_div_scale_f32 v178, s[18:19], v177, v177, 1.0
	v_rcp_f32_e32 v179, v178
	s_nop 0
	v_fma_f32 v180, -v178, v179, 1.0
	v_fmac_f32_e32 v179, v180, v179
	v_div_scale_f32 v180, vcc, 1.0, v177, 1.0
	v_mul_f32_e32 v181, v180, v179
	v_fma_f32 v182, -v178, v181, v180
	v_fmac_f32_e32 v181, v182, v179
	v_fma_f32 v178, -v178, v181, v180
	v_div_fmas_f32 v178, v178, v179, v181
	v_div_fixup_f32 v179, v178, v177, 1.0
	v_lshlrev_b32_e32 v166, 16, v46
	v_and_b32_e32 v167, 0xffff0000, v46
	v_lshlrev_b32_e32 v168, 16, v47
	v_and_b32_e32 v169, 0xffff0000, v47
	v_lshlrev_b32_e32 v170, 16, v48
	v_and_b32_e32 v171, 0xffff0000, v48
	v_lshlrev_b32_e32 v172, 16, v49
	v_and_b32_e32 v173, 0xffff0000, v49
	v_fma_f32 v110, v110, v179, -v166
	v_fma_f32 v111, v111, v179, -v167
	v_fma_f32 v112, v112, v179, -v168
	v_fma_f32 v113, v113, v179, -v169
	v_fma_f32 v114, v114, v179, -v170
	v_fma_f32 v115, v115, v179, -v171
	v_fma_f32 v116, v116, v179, -v172
	v_fma_f32 v117, v117, v179, -v173
	v_cvt_pk_bf16_f32 v184, v110, v111
	v_cvt_pk_bf16_f32 v185, v112, v113
	v_cvt_pk_bf16_f32 v186, v114, v115
	v_cvt_pk_bf16_f32 v187, v116, v117
	v_lshl_add_u32 v183, v174, 10, v5
	global_store_dwordx4 v183, v[184:187], s[16:17]
	s_nop 1
	v_add_u32_e32 v174, 2, v4
	v_subrev_u32_e32 v175, s6, v174
	v_max_i32_e32 v175, 0, v175
	v_add_u32_e32 v176, s6, v174
	v_min_i32_e32 v176, s9, v176
	v_sub_u32_e32 v176, v176, v175
	v_cvt_f32_u32_e32 v177, v176
	v_div_scale_f32 v178, s[18:19], v177, v177, 1.0
	v_rcp_f32_e32 v179, v178
	s_nop 0
	v_fma_f32 v180, -v178, v179, 1.0
	v_fmac_f32_e32 v179, v180, v179
	v_div_scale_f32 v180, vcc, 1.0, v177, 1.0
	v_mul_f32_e32 v181, v180, v179
	v_fma_f32 v182, -v178, v181, v180
	v_fmac_f32_e32 v181, v182, v179
	v_fma_f32 v178, -v178, v181, v180
	v_div_fmas_f32 v178, v178, v179, v181
	v_div_fixup_f32 v179, v178, v177, 1.0
	v_lshlrev_b32_e32 v166, 16, v50
	v_and_b32_e32 v167, 0xffff0000, v50
	v_lshlrev_b32_e32 v168, 16, v51
	v_and_b32_e32 v169, 0xffff0000, v51
	v_lshlrev_b32_e32 v170, 16, v52
	v_and_b32_e32 v171, 0xffff0000, v52
	v_lshlrev_b32_e32 v172, 16, v53
	v_and_b32_e32 v173, 0xffff0000, v53
	v_fma_f32 v118, v118, v179, -v166
	v_fma_f32 v119, v119, v179, -v167
	v_fma_f32 v120, v120, v179, -v168
	v_fma_f32 v121, v121, v179, -v169
; #define GAS __attribute__((address_space(1)))
; __device__ __forceinline__ unsigned pk2(float lo, float hi) { unsigned r; asm("v_cvt_pk_bf16_f32 %0, %1, %2" : "=v"(r) : "v"(lo), "v"(hi)); return r; }
; __device__ __forceinline__ void prep_phase(Frame& F, CArgs a, int l, unsigned long long& tm_acc) {
;     ...
;             const u32x4 sv = *(const GAS u32x4*)(zc + (size_t)t * DIN);
;             const float inv = 1.0f / (float)cnt;
;             u32x4 o; o.x = pk2(s[0] * inv - bflo(sv.x), s[1] * inv - bfhi(sv.x)); o.y = pk2(s[2] * inv - bflo(sv.y), s[3] * inv - bfhi(sv.y));
;             o.z = pk2(s[4] * inv - bflo(sv.z), s[5] * inv - bfhi(sv.z)); o.w = pk2(s[6] * inv - bflo(sv.w), s[7] * inv - bfhi(sv.w));
;             *(GAS u32x4*)(P + (size_t)row * 512 + cg * 8) = o;
	v_fma_f32 v122, v122, v179, -v170
	v_fma_f32 v123, v123, v179, -v171
	v_fma_f32 v124, v124, v179, -v172
	v_fma_f32 v125, v125, v179, -v173
	v_cvt_pk_bf16_f32 v184, v118, v119
	v_cvt_pk_bf16_f32 v185, v120, v121
	v_cvt_pk_bf16_f32 v186, v122, v123
	v_cvt_pk_bf16_f32 v187, v124, v125
	v_lshl_add_u32 v183, v174, 10, v5
	global_store_dwordx4 v183, v[184:187], s[16:17]
	s_nop 1
	v_add_u32_e32 v174, 3, v4
	v_subrev_u32_e32 v175, s6, v174
	v_max_i32_e32 v175, 0, v175
	v_add_u32_e32 v176, s6, v174
	v_min_i32_e32 v176, s9, v176
	v_sub_u32_e32 v176, v176, v175
	v_cvt_f32_u32_e32 v177, v176
	v_div_scale_f32 v178, s[18:19], v177, v177, 1.0
	v_rcp_f32_e32 v179, v178
	s_nop 0
	v_fma_f32 v180, -v178, v179, 1.0
	v_fmac_f32_e32 v179, v180, v179
	v_div_scale_f32 v180, vcc, 1.0, v177, 1.0
	v_mul_f32_e32 v181, v180, v179
	v_fma_f32 v182, -v178, v181, v180
	v_fmac_f32_e32 v181, v182, v179
	v_fma_f32 v178, -v178, v181, v180
	v_div_fmas_f32 v178, v178, v179, v181
	v_div_fixup_f32 v179, v178, v177, 1.0
	v_lshlrev_b32_e32 v166, 16, v54
	v_and_b32_e32 v167, 0xffff0000, v54
	v_lshlrev_b32_e32 v168, 16, v55
	v_and_b32_e32 v169, 0xffff0000, v55
	v_lshlrev_b32_e32 v170, 16, v56
	v_and_b32_e32 v171, 0xffff0000, v56
	v_lshlrev_b32_e32 v172, 16, v57
	v_and_b32_e32 v173, 0xffff0000, v57
	v_fma_f32 v126, v126, v179, -v166
	v_fma_f32 v127, v127, v179, -v167
	v_fma_f32 v128, v128, v179, -v168
	v_fma_f32 v129, v129, v179, -v169
	v_fma_f32 v130, v130, v179, -v170
	v_fma_f32 v131, v131, v179, -v171
	v_fma_f32 v132, v132, v179, -v172
	v_fma_f32 v133, v133, v179, -v173
	v_cvt_pk_bf16_f32 v184, v126, v127
	v_cvt_pk_bf16_f32 v185, v128, v129
	v_cvt_pk_bf16_f32 v186, v130, v131
	v_cvt_pk_bf16_f32 v187, v132, v133
	v_lshl_add_u32 v183, v174, 10, v5
	global_store_dwordx4 v183, v[184:187], s[16:17]
	s_nop 1
	v_add_u32_e32 v174, 4, v4
	v_subrev_u32_e32 v175, s6, v174
	v_max_i32_e32 v175, 0, v175
	v_add_u32_e32 v176, s6, v174
	v_min_i32_e32 v176, s9, v176
	v_sub_u32_e32 v176, v176, v175
	v_cvt_f32_u32_e32 v177, v176
	v_div_scale_f32 v178, s[18:19], v177, v177, 1.0
	v_rcp_f32_e32 v179, v178
	s_nop 0
	v_fma_f32 v180, -v178, v179, 1.0
	v_fmac_f32_e32 v179, v180, v179
	v_div_scale_f32 v180, vcc, 1.0, v177, 1.0
	v_mul_f32_e32 v181, v180, v179
	v_fma_f32 v182, -v178, v181, v180
	v_fmac_f32_e32 v181, v182, v179
	v_fma_f32 v178, -v178, v181, v180
	v_div_fmas_f32 v178, v178, v179, v181
	v_div_fixup_f32 v179, v178, v177, 1.0
	v_lshlrev_b32_e32 v166, 16, v58
	v_and_b32_e32 v167, 0xffff0000, v58
	v_lshlrev_b32_e32 v168, 16, v59
	v_and_b32_e32 v169, 0xffff0000, v59
	v_lshlrev_b32_e32 v170, 16, v60
	v_and_b32_e32 v171, 0xffff0000, v60
	v_lshlrev_b32_e32 v172, 16, v61
	v_and_b32_e32 v173, 0xffff0000, v61
	v_fma_f32 v134, v134, v179, -v166
	v_fma_f32 v135, v135, v179, -v167
	v_fma_f32 v136, v136, v179, -v168
	v_fma_f32 v137, v137, v179, -v169
	v_fma_f32 v138, v138, v179, -v170
	v_fma_f32 v139, v139, v179, -v171
	v_fma_f32 v140, v140, v179, -v172
	v_fma_f32 v141, v141, v179, -v173
	v_cvt_pk_bf16_f32 v184, v134, v135
	v_cvt_pk_bf16_f32 v185, v136, v137
	v_cvt_pk_bf16_f32 v186, v138, v139
	v_cvt_pk_bf16_f32 v187, v140, v141
	v_lshl_add_u32 v183, v174, 10, v5
	global_store_dwordx4 v183, v[184:187], s[16:17]
	s_nop 1
	v_add_u32_e32 v174, 5, v4
	v_subrev_u32_e32 v175, s6, v174
	v_max_i32_e32 v175, 0, v175
	v_add_u32_e32 v176, s6, v174
	v_min_i32_e32 v176, s9, v176
	v_sub_u32_e32 v176, v176, v175
	v_cvt_f32_u32_e32 v177, v176
	v_div_scale_f32 v178, s[18:19], v177, v177, 1.0
	v_rcp_f32_e32 v179, v178
	s_nop 0
	v_fma_f32 v180, -v178, v179, 1.0
	v_fmac_f32_e32 v179, v180, v179
	v_div_scale_f32 v180, vcc, 1.0, v177, 1.0
	v_mul_f32_e32 v181, v180, v179
	v_fma_f32 v182, -v178, v181, v180
	v_fmac_f32_e32 v181, v182, v179
	v_fma_f32 v178, -v178, v181, v180
	v_div_fmas_f32 v178, v178, v179, v181
	v_div_fixup_f32 v179, v178, v177, 1.0
	v_lshlrev_b32_e32 v166, 16, v62
	v_and_b32_e32 v167, 0xffff0000, v62
	v_lshlrev_b32_e32 v168, 16, v63
	v_and_b32_e32 v169, 0xffff0000, v63
	v_lshlrev_b32_e32 v170, 16, v64
	v_and_b32_e32 v171, 0xffff0000, v64
	v_lshlrev_b32_e32 v172, 16, v65
	v_and_b32_e32 v173, 0xffff0000, v65
	v_fma_f32 v142, v142, v179, -v166
; #define GAS __attribute__((address_space(1)))
; __device__ __forceinline__ unsigned pk2(float lo, float hi) { unsigned r; asm("v_cvt_pk_bf16_f32 %0, %1, %2" : "=v"(r) : "v"(lo), "v"(hi)); return r; }
; __device__ __forceinline__ void prep_phase(Frame& F, CArgs a, int l, unsigned long long& tm_acc) {
;     ...
;             const u32x4 sv = *(const GAS u32x4*)(zc + (size_t)t * DIN);
;             const float inv = 1.0f / (float)cnt;
;             u32x4 o; o.x = pk2(s[0] * inv - bflo(sv.x), s[1] * inv - bfhi(sv.x)); o.y = pk2(s[2] * inv - bflo(sv.y), s[3] * inv - bfhi(sv.y));
;             o.z = pk2(s[4] * inv - bflo(sv.z), s[5] * inv - bfhi(sv.z)); o.w = pk2(s[6] * inv - bflo(sv.w), s[7] * inv - bfhi(sv.w));
;             *(GAS u32x4*)(P + (size_t)row * 512 + cg * 8) = o;
	v_fma_f32 v143, v143, v179, -v167
	v_fma_f32 v144, v144, v179, -v168
	v_fma_f32 v145, v145, v179, -v169
	v_fma_f32 v146, v146, v179, -v170
	v_fma_f32 v147, v147, v179, -v171
	v_fma_f32 v148, v148, v179, -v172
	v_fma_f32 v149, v149, v179, -v173
	v_cvt_pk_bf16_f32 v184, v142, v143
	v_cvt_pk_bf16_f32 v185, v144, v145
	v_cvt_pk_bf16_f32 v186, v146, v147
	v_cvt_pk_bf16_f32 v187, v148, v149
	v_lshl_add_u32 v183, v174, 10, v5
	global_store_dwordx4 v183, v[184:187], s[16:17]
	s_nop 1
	v_add_u32_e32 v174, 6, v4
	v_subrev_u32_e32 v175, s6, v174
	v_max_i32_e32 v175, 0, v175
	v_add_u32_e32 v176, s6, v174
	v_min_i32_e32 v176, s9, v176
	v_sub_u32_e32 v176, v176, v175
	v_cvt_f32_u32_e32 v177, v176
	v_div_scale_f32 v178, s[18:19], v177, v177, 1.0
	v_rcp_f32_e32 v179, v178
	s_nop 0
	v_fma_f32 v180, -v178, v179, 1.0
	v_fmac_f32_e32 v179, v180, v179
	v_div_scale_f32 v180, vcc, 1.0, v177, 1.0
	v_mul_f32_e32 v181, v180, v179
	v_fma_f32 v182, -v178, v181, v180
	v_fmac_f32_e32 v181, v182, v179
	v_fma_f32 v178, -v178, v181, v180
	v_div_fmas_f32 v178, v178, v179, v181
	v_div_fixup_f32 v179, v178, v177, 1.0
	v_lshlrev_b32_e32 v166, 16, v66
	v_and_b32_e32 v167, 0xffff0000, v66
	v_lshlrev_b32_e32 v168, 16, v67
	v_and_b32_e32 v169, 0xffff0000, v67
	v_lshlrev_b32_e32 v170, 16, v68
	v_and_b32_e32 v171, 0xffff0000, v68
	v_lshlrev_b32_e32 v172, 16, v69
	v_and_b32_e32 v173, 0xffff0000, v69
	v_fma_f32 v150, v150, v179, -v166
	v_fma_f32 v151, v151, v179, -v167
	v_fma_f32 v152, v152, v179, -v168
	v_fma_f32 v153, v153, v179, -v169
	v_fma_f32 v154, v154, v179, -v170
	v_fma_f32 v155, v155, v179, -v171
	v_fma_f32 v156, v156, v179, -v172
	v_fma_f32 v157, v157, v179, -v173
	v_cvt_pk_bf16_f32 v184, v150, v151
	v_cvt_pk_bf16_f32 v185, v152, v153
	v_cvt_pk_bf16_f32 v186, v154, v155
	v_cvt_pk_bf16_f32 v187, v156, v157
	v_lshl_add_u32 v183, v174, 10, v5
	global_store_dwordx4 v183, v[184:187], s[16:17]
	s_nop 1
	v_add_u32_e32 v174, 7, v4
	v_subrev_u32_e32 v175, s6, v174
	v_max_i32_e32 v175, 0, v175
	v_add_u32_e32 v176, s6, v174
	v_min_i32_e32 v176, s9, v176
	v_sub_u32_e32 v176, v176, v175
	v_cvt_f32_u32_e32 v177, v176
	v_div_scale_f32 v178, s[18:19], v177, v177, 1.0
	v_rcp_f32_e32 v179, v178
	s_nop 0
	v_fma_f32 v180, -v178, v179, 1.0
	v_fmac_f32_e32 v179, v180, v179
	v_div_scale_f32 v180, vcc, 1.0, v177, 1.0
	v_mul_f32_e32 v181, v180, v179
	v_fma_f32 v182, -v178, v181, v180
	v_fmac_f32_e32 v181, v182, v179
	v_fma_f32 v178, -v178, v181, v180
	v_div_fmas_f32 v178, v178, v179, v181
	v_div_fixup_f32 v179, v178, v177, 1.0
	v_lshlrev_b32_e32 v166, 16, v70
	v_and_b32_e32 v167, 0xffff0000, v70
	v_lshlrev_b32_e32 v168, 16, v71
	v_and_b32_e32 v169, 0xffff0000, v71
	v_lshlrev_b32_e32 v170, 16, v72
	v_and_b32_e32 v171, 0xffff0000, v72
	v_lshlrev_b32_e32 v172, 16, v73
	v_and_b32_e32 v173, 0xffff0000, v73
	v_fma_f32 v158, v158, v179, -v166
	v_fma_f32 v159, v159, v179, -v167
	v_fma_f32 v160, v160, v179, -v168
	v_fma_f32 v161, v161, v179, -v169
	v_fma_f32 v162, v162, v179, -v170
	v_fma_f32 v163, v163, v179, -v171
	v_fma_f32 v164, v164, v179, -v172
	v_fma_f32 v165, v165, v179, -v173
	v_cvt_pk_bf16_f32 v184, v158, v159
	v_cvt_pk_bf16_f32 v185, v160, v161
	v_cvt_pk_bf16_f32 v186, v162, v163
	v_cvt_pk_bf16_f32 v187, v164, v165
	v_lshl_add_u32 v183, v174, 10, v5
	global_store_dwordx4 v183, v[184:187], s[16:17]
	s_nop 1
.Lhp_done:
	s_nop 0
	v_readlane_b32 s4, v201, 0
	v_readlane_b32 s5, v201, 1
	v_readlane_b32 s6, v201, 2
	v_readlane_b32 s7, v201, 3
	v_readlane_b32 s8, v201, 4
	v_readlane_b32 s9, v201, 5
	v_readlane_b32 s10, v201, 6
	v_readlane_b32 s11, v201, 7
	v_readlane_b32 s12, v201, 8
	v_readlane_b32 s13, v201, 9
	v_readlane_b32 s14, v201, 10
	v_readlane_b32 s15, v201, 11
	v_readlane_b32 s16, v201, 12
	v_readlane_b32 s17, v201, 13
	v_readlane_b32 s18, v201, 14
	v_readlane_b32 s19, v201, 15
	v_readlane_b32 s20, v201, 16
	v_readlane_b32 s21, v201, 17
	v_readlane_b32 s22, v201, 18
	v_readlane_b32 s23, v201, 19
	v_readlane_b32 s24, v201, 20
	v_readlane_b32 s25, v201, 21
	v_readlane_b32 s26, v201, 22
	v_readlane_b32 s27, v201, 23
	v_readlane_b32 s28, v201, 24
	v_readlane_b32 s29, v201, 25
	v_readlane_b32 s30, v201, 26
	v_readlane_b32 s31, v201, 27
	s_nop 3
